# back-edge block placed ahead of the closing vmcnt wait as well (instructions between last wait and barrier are not free)
# speedup vs baseline: 1.0035x; 1.0026x over previous
.Lprio_skip4:
.LBB0_655:
	ds_read_b128 v[120:123], v230
	ds_read_b128 v[132:135], v230 offset:1024
	ds_read_b128 v[136:139], v230 offset:2048
	ds_read_b128 v[140:143], v230 offset:3072
	ds_read_b128 v[144:147], v231
	ds_read_b128 v[148:151], v231 offset:1024
	ds_read_b128 v[152:155], v231 offset:2048
	ds_read_b128 v[156:159], v231 offset:3072
	s_add_u32 s28, s0, s2
	s_addc_u32 s29, s1, s3
	s_cmpk_eq_i32 s2, 0x1000
	s_cselect_b32 s30, 0, s2
	s_cselect_b32 s31, 0, s3
	s_cselect_b32 s28, s57, s28
	s_cselect_b32 s29, s7, s29
	s_add_u32 s30, s10, s30
	s_addc_u32 s31, s11, s31
	s_add_u32 s98, s2, s86
	s_addc_u32 s99, s3, s87
	s_add_i32 m0, s85, 0x8000
	v_lshl_add_u64 v[204:205], v[192:193], 0, s[98:99]
	ds_read_b128 v[160:163], v232
	ds_read_b128 v[164:167], v232 offset:1024
	ds_read_b128 v[168:171], v232 offset:2048
	ds_read_b128 v[172:175], v232 offset:3072
	ds_read_b128 v[176:179], v232 offset:4096
	ds_read_b128 v[180:183], v232 offset:5120
	ds_read_b128 v[196:199], v232 offset:6144
	ds_read_b128 v[200:203], v232 offset:7168
	global_load_lds_dwordx4 v[204:205], off
	s_add_u32 s98, s98, 0x20000
	s_addc_u32 s99, s99, 0
	s_add_i32 m0, s85, 0x9000
	v_lshl_add_u64 v[204:205], v[192:193], 0, s[98:99]
	global_load_lds_dwordx4 v[204:205], off
	s_add_u32 s98, s98, 0x20000
	s_addc_u32 s99, s99, 0
	s_add_i32 m0, s85, 0xa000
	v_lshl_add_u64 v[204:205], v[192:193], 0, s[98:99]
	global_load_lds_dwordx4 v[204:205], off
	s_add_u32 s98, s98, 0x20000
	s_addc_u32 s99, s99, 0
	s_add_i32 m0, s85, 0xb000
	v_lshl_add_u64 v[204:205], v[192:193], 0, s[98:99]
	global_load_lds_dwordx4 v[204:205], off
	s_waitcnt vmcnt(8)
	s_waitcnt lgkmcnt(0)
	s_barrier
	s_waitcnt lgkmcnt(0)
	v_mfma_f32_16x16x32_bf16 v[128:131], v[120:123], v[160:163], v[128:131]
	v_mfma_f32_16x16x32_bf16 v[124:127], v[136:139], v[160:163], v[124:127]
	v_mfma_f32_16x16x32_bf16 v[108:111], v[120:123], v[168:171], v[108:111]
	v_mfma_f32_16x16x32_bf16 v[104:107], v[136:139], v[168:171], v[104:107]
	v_mfma_f32_16x16x32_bf16 v[92:95], v[120:123], v[176:179], v[92:95]
	v_mfma_f32_16x16x32_bf16 v[88:91], v[136:139], v[176:179], v[88:91]
	v_mfma_f32_16x16x32_bf16 v[76:79], v[120:123], v[196:199], v[76:79]
	v_mfma_f32_16x16x32_bf16 v[72:75], v[136:139], v[196:199], v[72:75]
	v_mfma_f32_16x16x32_bf16 v[128:131], v[132:135], v[164:167], v[128:131]
	v_mfma_f32_16x16x32_bf16 v[124:127], v[140:143], v[164:167], v[124:127]
	v_mfma_f32_16x16x32_bf16 v[108:111], v[132:135], v[172:175], v[108:111]
	v_mfma_f32_16x16x32_bf16 v[104:107], v[140:143], v[172:175], v[104:107]
	v_mfma_f32_16x16x32_bf16 v[92:95], v[132:135], v[180:183], v[92:95]
	v_mfma_f32_16x16x32_bf16 v[88:91], v[140:143], v[180:183], v[88:91]
	v_mfma_f32_16x16x32_bf16 v[76:79], v[132:135], v[200:203], v[76:79]
	v_mfma_f32_16x16x32_bf16 v[72:75], v[140:143], v[200:203], v[72:75]
	v_mfma_f32_16x16x32_bf16 v[116:119], v[144:147], v[160:163], v[116:119]
	v_mfma_f32_16x16x32_bf16 v[112:115], v[152:155], v[160:163], v[112:115]
	v_mfma_f32_16x16x32_bf16 v[100:103], v[144:147], v[168:171], v[100:103]
	v_mfma_f32_16x16x32_bf16 v[96:99], v[152:155], v[168:171], v[96:99]
	v_mfma_f32_16x16x32_bf16 v[84:87], v[144:147], v[176:179], v[84:87]
	v_mfma_f32_16x16x32_bf16 v[80:83], v[152:155], v[176:179], v[80:83]
	v_mfma_f32_16x16x32_bf16 v[68:71], v[144:147], v[196:199], v[68:71]
	v_mfma_f32_16x16x32_bf16 v[64:67], v[152:155], v[196:199], v[64:67]
	v_mfma_f32_16x16x32_bf16 v[116:119], v[148:151], v[164:167], v[116:119]
	v_mfma_f32_16x16x32_bf16 v[112:115], v[156:159], v[164:167], v[112:115]
	v_mfma_f32_16x16x32_bf16 v[100:103], v[148:151], v[172:175], v[100:103]
	v_mfma_f32_16x16x32_bf16 v[96:99], v[156:159], v[172:175], v[96:99]
	v_mfma_f32_16x16x32_bf16 v[84:87], v[148:151], v[180:183], v[84:87]
	v_mfma_f32_16x16x32_bf16 v[80:83], v[156:159], v[180:183], v[80:83]
	v_mfma_f32_16x16x32_bf16 v[68:71], v[148:151], v[200:203], v[68:71]
	v_mfma_f32_16x16x32_bf16 v[64:67], v[156:159], v[200:203], v[64:67]
	s_barrier
	s_mov_b32 m0, s50
	v_lshl_add_u64 v[204:205], s[28:29], 0, v[188:189]
	s_add_u32 s60, s28, 0x80000
	ds_read_b128 v[160:163], v232 offset:16384
	ds_read_b128 v[164:167], v232 offset:17408
	ds_read_b128 v[168:171], v232 offset:18432
	ds_read_b128 v[172:175], v232 offset:19456
	ds_read_b128 v[176:179], v232 offset:20480
	ds_read_b128 v[180:183], v232 offset:21504
	ds_read_b128 v[196:199], v232 offset:22528
	ds_read_b128 v[200:203], v232 offset:23552
	global_load_lds_dwordx4 v[204:205], off
	v_lshl_add_u64 v[206:207], s[28:29], 0, v[184:185]
	s_mov_b32 m0, s51
	s_addc_u32 s61, s29, 0
	global_load_lds_dwordx4 v[206:207], off
	v_lshl_add_u64 v[208:209], s[60:61], 0, v[188:189]
	s_mov_b32 m0, s52
	global_load_lds_dwordx4 v[208:209], off
	v_lshl_add_u64 v[208:209], s[60:61], 0, v[184:185]
	s_mov_b32 m0, s53
	s_nop 0
	global_load_lds_dwordx4 v[208:209], off
	s_waitcnt vmcnt(8)
	s_waitcnt lgkmcnt(0)
	s_barrier
	s_waitcnt lgkmcnt(0)
	v_mfma_f32_16x16x32_bf16 v[60:63], v[120:123], v[160:163], v[60:63]
	v_mfma_f32_16x16x32_bf16 v[56:59], v[136:139], v[160:163], v[56:59]
	v_mfma_f32_16x16x32_bf16 v[44:47], v[120:123], v[168:171], v[44:47]
	v_mfma_f32_16x16x32_bf16 v[40:43], v[136:139], v[168:171], v[40:43]
	v_mfma_f32_16x16x32_bf16 v[28:31], v[120:123], v[176:179], v[28:31]
	v_mfma_f32_16x16x32_bf16 v[24:27], v[136:139], v[176:179], v[24:27]
	v_mfma_f32_16x16x32_bf16 v[12:15], v[120:123], v[196:199], v[12:15]
	v_mfma_f32_16x16x32_bf16 v[8:11], v[136:139], v[196:199], v[8:11]
	v_mfma_f32_16x16x32_bf16 v[60:63], v[132:135], v[164:167], v[60:63]
	v_mfma_f32_16x16x32_bf16 v[56:59], v[140:143], v[164:167], v[56:59]
	v_mfma_f32_16x16x32_bf16 v[44:47], v[132:135], v[172:175], v[44:47]
	v_mfma_f32_16x16x32_bf16 v[40:43], v[140:143], v[172:175], v[40:43]
	v_mfma_f32_16x16x32_bf16 v[28:31], v[132:135], v[180:183], v[28:31]
	v_mfma_f32_16x16x32_bf16 v[24:27], v[140:143], v[180:183], v[24:27]
	v_mfma_f32_16x16x32_bf16 v[12:15], v[132:135], v[200:203], v[12:15]
	v_mfma_f32_16x16x32_bf16 v[8:11], v[140:143], v[200:203], v[8:11]
	v_mfma_f32_16x16x32_bf16 v[52:55], v[144:147], v[160:163], v[52:55]
	v_mfma_f32_16x16x32_bf16 v[48:51], v[152:155], v[160:163], v[48:51]
	v_mfma_f32_16x16x32_bf16 v[36:39], v[144:147], v[168:171], v[36:39]
	v_mfma_f32_16x16x32_bf16 v[32:35], v[152:155], v[168:171], v[32:35]
	v_mfma_f32_16x16x32_bf16 v[20:23], v[144:147], v[176:179], v[20:23]
	v_mfma_f32_16x16x32_bf16 v[16:19], v[152:155], v[176:179], v[16:19]
	v_mfma_f32_16x16x32_bf16 v[4:7], v[144:147], v[196:199], v[4:7]
	v_mfma_f32_16x16x32_bf16 v[0:3], v[152:155], v[196:199], v[0:3]
	v_mfma_f32_16x16x32_bf16 v[52:55], v[148:151], v[164:167], v[52:55]
	v_mfma_f32_16x16x32_bf16 v[48:51], v[156:159], v[164:167], v[48:51]
	v_mfma_f32_16x16x32_bf16 v[36:39], v[148:151], v[172:175], v[36:39]
	v_mfma_f32_16x16x32_bf16 v[32:35], v[156:159], v[172:175], v[32:35]
	v_mfma_f32_16x16x32_bf16 v[20:23], v[148:151], v[180:183], v[20:23]
	v_mfma_f32_16x16x32_bf16 v[16:19], v[156:159], v[180:183], v[16:19]
	v_mfma_f32_16x16x32_bf16 v[4:7], v[148:151], v[200:203], v[4:7]
	v_mfma_f32_16x16x32_bf16 v[0:3], v[156:159], v[200:203], v[0:3]
	s_waitcnt vmcnt(4)
	s_barrier
	ds_read_b128 v[120:123], v234
	ds_read_b128 v[132:135], v234 offset:1024
	ds_read_b128 v[136:139], v234 offset:2048
	ds_read_b128 v[140:143], v234 offset:3072
	ds_read_b128 v[144:147], v235
	ds_read_b128 v[148:151], v235 offset:1024
	ds_read_b128 v[152:155], v235 offset:2048
	ds_read_b128 v[156:159], v235 offset:3072
	s_add_u32 s98, s30, s96
	s_addc_u32 s99, s31, s97
	s_add_i32 m0, s85, 0
	v_lshl_add_u64 v[212:213], s[98:99], 0, v[190:191]
	ds_read_b128 v[160:163], v232 offset:32768
	ds_read_b128 v[164:167], v232 offset:33792
	ds_read_b128 v[168:171], v232 offset:34816
	ds_read_b128 v[172:175], v232 offset:35840
	ds_read_b128 v[176:179], v232 offset:36864
	ds_read_b128 v[180:183], v232 offset:37888
	ds_read_b128 v[196:199], v232 offset:38912
	ds_read_b128 v[200:203], v232 offset:39936
	global_load_lds_dwordx4 v[212:213], off
	s_add_u32 s98, s98, 0x20000
	s_addc_u32 s99, s99, 0
	s_add_i32 m0, s85, 0x1000
	v_lshl_add_u64 v[212:213], s[98:99], 0, v[190:191]
	global_load_lds_dwordx4 v[212:213], off
	s_add_u32 s98, s98, 0x20000
	s_addc_u32 s99, s99, 0
	s_add_i32 m0, s85, 0x2000
	v_lshl_add_u64 v[212:213], s[98:99], 0, v[190:191]
	global_load_lds_dwordx4 v[212:213], off
	s_add_u32 s98, s98, 0x20000
	s_addc_u32 s99, s99, 0
	s_add_i32 m0, s85, 0x3000
	v_lshl_add_u64 v[212:213], s[98:99], 0, v[190:191]
	global_load_lds_dwordx4 v[212:213], off
	s_waitcnt vmcnt(8)
	s_waitcnt lgkmcnt(0)
	s_barrier
	s_waitcnt lgkmcnt(0)
	v_mfma_f32_16x16x32_bf16 v[128:131], v[120:123], v[160:163], v[128:131]
	v_mfma_f32_16x16x32_bf16 v[124:127], v[136:139], v[160:163], v[124:127]
	v_mfma_f32_16x16x32_bf16 v[108:111], v[120:123], v[168:171], v[108:111]
	v_mfma_f32_16x16x32_bf16 v[104:107], v[136:139], v[168:171], v[104:107]
	v_mfma_f32_16x16x32_bf16 v[92:95], v[120:123], v[176:179], v[92:95]
	v_mfma_f32_16x16x32_bf16 v[88:91], v[136:139], v[176:179], v[88:91]
	v_mfma_f32_16x16x32_bf16 v[76:79], v[120:123], v[196:199], v[76:79]
	v_mfma_f32_16x16x32_bf16 v[72:75], v[136:139], v[196:199], v[72:75]
	v_mfma_f32_16x16x32_bf16 v[128:131], v[132:135], v[164:167], v[128:131]
	v_mfma_f32_16x16x32_bf16 v[124:127], v[140:143], v[164:167], v[124:127]
	v_mfma_f32_16x16x32_bf16 v[108:111], v[132:135], v[172:175], v[108:111]
	v_mfma_f32_16x16x32_bf16 v[104:107], v[140:143], v[172:175], v[104:107]
	v_mfma_f32_16x16x32_bf16 v[92:95], v[132:135], v[180:183], v[92:95]
	v_mfma_f32_16x16x32_bf16 v[88:91], v[140:143], v[180:183], v[88:91]
	v_mfma_f32_16x16x32_bf16 v[76:79], v[132:135], v[200:203], v[76:79]
	v_mfma_f32_16x16x32_bf16 v[72:75], v[140:143], v[200:203], v[72:75]
	v_mfma_f32_16x16x32_bf16 v[116:119], v[144:147], v[160:163], v[116:119]
	v_mfma_f32_16x16x32_bf16 v[112:115], v[152:155], v[160:163], v[112:115]
	v_mfma_f32_16x16x32_bf16 v[100:103], v[144:147], v[168:171], v[100:103]
	v_mfma_f32_16x16x32_bf16 v[96:99], v[152:155], v[168:171], v[96:99]
	v_mfma_f32_16x16x32_bf16 v[84:87], v[144:147], v[176:179], v[84:87]
	v_mfma_f32_16x16x32_bf16 v[80:83], v[152:155], v[176:179], v[80:83]
	v_mfma_f32_16x16x32_bf16 v[68:71], v[144:147], v[196:199], v[68:71]
	v_mfma_f32_16x16x32_bf16 v[64:67], v[152:155], v[196:199], v[64:67]
	v_mfma_f32_16x16x32_bf16 v[116:119], v[148:151], v[164:167], v[116:119]
	v_mfma_f32_16x16x32_bf16 v[112:115], v[156:159], v[164:167], v[112:115]
	v_mfma_f32_16x16x32_bf16 v[100:103], v[148:151], v[172:175], v[100:103]
	v_mfma_f32_16x16x32_bf16 v[96:99], v[156:159], v[172:175], v[96:99]
	v_mfma_f32_16x16x32_bf16 v[84:87], v[148:151], v[180:183], v[84:87]
	v_mfma_f32_16x16x32_bf16 v[80:83], v[156:159], v[180:183], v[80:83]
	v_mfma_f32_16x16x32_bf16 v[68:71], v[148:151], v[200:203], v[68:71]
	v_mfma_f32_16x16x32_bf16 v[64:67], v[156:159], v[200:203], v[64:67]
	s_barrier
	s_mov_b32 m0, s55
	v_lshl_add_u64 v[204:205], v[204:205], 0, s[18:19]
	ds_read_b128 v[160:163], v232 offset:49152
	ds_read_b128 v[164:167], v232 offset:50176
	ds_read_b128 v[168:171], v232 offset:51200
	ds_read_b128 v[172:175], v232 offset:52224
	ds_read_b128 v[176:179], v232 offset:53248
	ds_read_b128 v[180:183], v232 offset:54272
	ds_read_b128 v[196:199], v232 offset:55296
	ds_read_b128 v[200:203], v232 offset:56320
	global_load_lds_dwordx4 v[204:205], off
	s_add_i32 m0, s55, 0x2000
	s_add_u32 s28, s28, 0x80080
	v_lshl_add_u64 v[204:205], v[206:207], 0, s[18:19]
	s_addc_u32 s29, s29, 0
	s_add_i32 s30, s54, s37
	global_load_lds_dwordx4 v[204:205], off
	v_lshl_add_u64 v[204:205], s[28:29], 0, v[188:189]
	s_mov_b32 m0, s30
	s_nop 0
	global_load_lds_dwordx4 v[204:205], off
	v_lshl_add_u64 v[204:205], s[28:29], 0, v[184:185]
	s_add_i32 m0, s30, 0x2000
	s_nop 0
	global_load_lds_dwordx4 v[204:205], off
	s_waitcnt vmcnt(8)
	s_waitcnt lgkmcnt(0)
	s_barrier
	s_waitcnt lgkmcnt(0)
	v_mfma_f32_16x16x32_bf16 v[60:63], v[120:123], v[160:163], v[60:63]
	v_mfma_f32_16x16x32_bf16 v[56:59], v[136:139], v[160:163], v[56:59]
	v_mfma_f32_16x16x32_bf16 v[44:47], v[120:123], v[168:171], v[44:47]
	v_mfma_f32_16x16x32_bf16 v[40:43], v[136:139], v[168:171], v[40:43]
	v_mfma_f32_16x16x32_bf16 v[28:31], v[120:123], v[176:179], v[28:31]
	v_mfma_f32_16x16x32_bf16 v[24:27], v[136:139], v[176:179], v[24:27]
	v_mfma_f32_16x16x32_bf16 v[12:15], v[120:123], v[196:199], v[12:15]
	v_mfma_f32_16x16x32_bf16 v[8:11], v[136:139], v[196:199], v[8:11]
	v_mfma_f32_16x16x32_bf16 v[60:63], v[132:135], v[164:167], v[60:63]
	v_mfma_f32_16x16x32_bf16 v[56:59], v[140:143], v[164:167], v[56:59]
	v_mfma_f32_16x16x32_bf16 v[44:47], v[132:135], v[172:175], v[44:47]
	v_mfma_f32_16x16x32_bf16 v[40:43], v[140:143], v[172:175], v[40:43]
	v_mfma_f32_16x16x32_bf16 v[28:31], v[132:135], v[180:183], v[28:31]
	v_mfma_f32_16x16x32_bf16 v[24:27], v[140:143], v[180:183], v[24:27]
	v_mfma_f32_16x16x32_bf16 v[12:15], v[132:135], v[200:203], v[12:15]
	v_mfma_f32_16x16x32_bf16 v[8:11], v[140:143], v[200:203], v[8:11]
	v_mfma_f32_16x16x32_bf16 v[52:55], v[144:147], v[160:163], v[52:55]
	v_mfma_f32_16x16x32_bf16 v[48:51], v[152:155], v[160:163], v[48:51]
	v_mfma_f32_16x16x32_bf16 v[36:39], v[144:147], v[168:171], v[36:39]
	v_mfma_f32_16x16x32_bf16 v[32:35], v[152:155], v[168:171], v[32:35]
	v_mfma_f32_16x16x32_bf16 v[20:23], v[144:147], v[176:179], v[20:23]
	v_mfma_f32_16x16x32_bf16 v[16:19], v[152:155], v[176:179], v[16:19]
	v_mfma_f32_16x16x32_bf16 v[4:7], v[144:147], v[196:199], v[4:7]
	v_mfma_f32_16x16x32_bf16 v[0:3], v[152:155], v[196:199], v[0:3]
	v_mfma_f32_16x16x32_bf16 v[52:55], v[148:151], v[164:167], v[52:55]
	v_mfma_f32_16x16x32_bf16 v[48:51], v[156:159], v[164:167], v[48:51]
	v_mfma_f32_16x16x32_bf16 v[36:39], v[148:151], v[172:175], v[36:39]
	v_mfma_f32_16x16x32_bf16 v[32:35], v[156:159], v[172:175], v[32:35]
	v_mfma_f32_16x16x32_bf16 v[20:23], v[148:151], v[180:183], v[20:23]
	v_mfma_f32_16x16x32_bf16 v[16:19], v[156:159], v[180:183], v[16:19]
	v_mfma_f32_16x16x32_bf16 v[4:7], v[148:151], v[200:203], v[4:7]
	v_mfma_f32_16x16x32_bf16 v[0:3], v[156:159], v[200:203], v[0:3]
	s_add_i32 s58, s58, 2
	s_add_u32 s2, s2, 0x100
	s_addc_u32 s3, s3, 0
	s_cmp_gt_u32 s58, 29
	s_waitcnt vmcnt(4)
	s_barrier
	s_cbranch_scc0 .LBB0_655
	s_setprio 0
	s_and_b64 vcc, exec, s[22:23]
	s_cbranch_vccz .LBB0_658
	s_barrier

.Lprio_skip5:
.LBB0_785:
	ds_read_b128 v[140:143], v148
	ds_read_b128 v[154:157], v148 offset:1024
	ds_read_b128 v[158:161], v148 offset:2048
	ds_read_b128 v[162:165], v148 offset:3072
	ds_read_b128 v[166:169], v149
	ds_read_b128 v[170:173], v149 offset:1024
	ds_read_b128 v[174:177], v149 offset:2048
	ds_read_b128 v[178:181], v149 offset:3072
	s_add_u32 s38, s36, 0xfff80080
	s_addc_u32 s39, s37, -1
	s_cmp_eq_u32 s75, 28
	s_cselect_b32 s41, s69, s39
	s_cselect_b32 s40, s70, s38
	s_cselect_b32 s39, s71, s74
	s_cselect_b32 s38, s72, s73
	s_sub_u32 s98, s36, 0x80000
	s_subb_u32 s99, s37, 0
	s_add_i32 m0, s85, 0x8000
	ds_read_b128 v[182:185], v150
	ds_read_b128 v[186:189], v150 offset:1024
	ds_read_b128 v[190:193], v150 offset:2048
	ds_read_b128 v[194:197], v150 offset:3072
	ds_read_b128 v[198:201], v150 offset:4096
	ds_read_b128 v[202:205], v150 offset:5120
	ds_read_b128 v[206:209], v150 offset:6144
	ds_read_b128 v[210:213], v150 offset:7168
	global_load_lds_dwordx4 v222, s[98:99]
	s_add_u32 s98, s98, 0x20000
	s_addc_u32 s99, s99, 0
	s_add_i32 m0, s85, 0x9000
	s_nop 0
	global_load_lds_dwordx4 v222, s[98:99]
	s_add_u32 s98, s98, 0x20000
	s_addc_u32 s99, s99, 0
	s_add_i32 m0, s85, 0xa000
	s_nop 0
	global_load_lds_dwordx4 v222, s[98:99]
	s_add_u32 s98, s98, 0x20000
	s_addc_u32 s99, s99, 0
	s_add_i32 m0, s85, 0xb000
	s_nop 0
	global_load_lds_dwordx4 v222, s[98:99]
	s_waitcnt vmcnt(8)
	s_waitcnt lgkmcnt(0)
	s_barrier
	s_waitcnt lgkmcnt(0)
	v_mfma_f32_16x16x32_bf16 v[124:127], v[140:143], v[182:185], v[124:127]
	v_mfma_f32_16x16x32_bf16 v[120:123], v[158:161], v[182:185], v[120:123]
	v_mfma_f32_16x16x32_bf16 v[112:115], v[140:143], v[190:193], v[112:115]
	v_mfma_f32_16x16x32_bf16 v[104:107], v[158:161], v[190:193], v[104:107]
	v_mfma_f32_16x16x32_bf16 v[96:99], v[140:143], v[198:201], v[96:99]
	v_mfma_f32_16x16x32_bf16 v[88:91], v[158:161], v[198:201], v[88:91]
	v_mfma_f32_16x16x32_bf16 v[80:83], v[140:143], v[206:209], v[80:83]
	v_mfma_f32_16x16x32_bf16 v[72:75], v[158:161], v[206:209], v[72:75]
	v_mfma_f32_16x16x32_bf16 v[124:127], v[154:157], v[186:189], v[124:127]
	v_mfma_f32_16x16x32_bf16 v[120:123], v[162:165], v[186:189], v[120:123]
	v_mfma_f32_16x16x32_bf16 v[112:115], v[154:157], v[194:197], v[112:115]
	v_mfma_f32_16x16x32_bf16 v[104:107], v[162:165], v[194:197], v[104:107]
	v_mfma_f32_16x16x32_bf16 v[96:99], v[154:157], v[202:205], v[96:99]
	v_mfma_f32_16x16x32_bf16 v[88:91], v[162:165], v[202:205], v[88:91]
	v_mfma_f32_16x16x32_bf16 v[80:83], v[154:157], v[210:213], v[80:83]
	v_mfma_f32_16x16x32_bf16 v[72:75], v[162:165], v[210:213], v[72:75]
	v_mfma_f32_16x16x32_bf16 v[116:119], v[166:169], v[182:185], v[116:119]
	v_mfma_f32_16x16x32_bf16 v[108:111], v[174:177], v[182:185], v[108:111]
	v_mfma_f32_16x16x32_bf16 v[100:103], v[166:169], v[190:193], v[100:103]
	v_mfma_f32_16x16x32_bf16 v[92:95], v[174:177], v[190:193], v[92:95]
	v_mfma_f32_16x16x32_bf16 v[84:87], v[166:169], v[198:201], v[84:87]
	v_mfma_f32_16x16x32_bf16 v[76:79], v[174:177], v[198:201], v[76:79]
	v_mfma_f32_16x16x32_bf16 v[68:71], v[166:169], v[206:209], v[68:71]
	v_mfma_f32_16x16x32_bf16 v[64:67], v[174:177], v[206:209], v[64:67]
	v_mfma_f32_16x16x32_bf16 v[116:119], v[170:173], v[186:189], v[116:119]
	v_mfma_f32_16x16x32_bf16 v[108:111], v[178:181], v[186:189], v[108:111]
	v_mfma_f32_16x16x32_bf16 v[100:103], v[170:173], v[194:197], v[100:103]
	v_mfma_f32_16x16x32_bf16 v[92:95], v[178:181], v[194:197], v[92:95]
	v_mfma_f32_16x16x32_bf16 v[84:87], v[170:173], v[202:205], v[84:87]
	v_mfma_f32_16x16x32_bf16 v[76:79], v[178:181], v[202:205], v[76:79]
	v_mfma_f32_16x16x32_bf16 v[68:71], v[170:173], v[210:213], v[68:71]
	v_mfma_f32_16x16x32_bf16 v[64:67], v[178:181], v[210:213], v[64:67]
	s_barrier
	s_add_i32 s76, s59, s5
	v_lshl_add_u64 v[144:145], s[38:39], 0, v[130:131]
	s_mov_b32 m0, s76
	ds_read_b128 v[182:185], v150 offset:16384
	ds_read_b128 v[186:189], v150 offset:17408
	ds_read_b128 v[190:193], v150 offset:18432
	ds_read_b128 v[194:197], v150 offset:19456
	ds_read_b128 v[198:201], v150 offset:20480
	ds_read_b128 v[202:205], v150 offset:21504
	ds_read_b128 v[206:209], v150 offset:22528
	ds_read_b128 v[210:213], v150 offset:23552
	global_load_lds_dwordx4 v[144:145], off
	s_add_i32 m0, s76, 0x2000
	s_add_u32 s76, s38, 0x80000
	v_lshl_add_u64 v[214:215], s[38:39], 0, v[134:135]
	s_addc_u32 s77, s39, 0
	s_add_i32 s78, s60, s5
	global_load_lds_dwordx4 v[214:215], off
	v_lshl_add_u64 v[216:217], s[76:77], 0, v[130:131]
	s_mov_b32 m0, s78
	global_load_lds_dwordx4 v[216:217], off
	v_lshl_add_u64 v[216:217], s[76:77], 0, v[134:135]
	s_add_i32 m0, s78, 0x2000
	s_nop 0
	global_load_lds_dwordx4 v[216:217], off
	s_waitcnt vmcnt(8)
	s_waitcnt lgkmcnt(0)
	s_barrier
	s_waitcnt lgkmcnt(0)
	v_mfma_f32_16x16x32_bf16 v[60:63], v[140:143], v[182:185], v[60:63]
	v_mfma_f32_16x16x32_bf16 v[56:59], v[158:161], v[182:185], v[56:59]
	v_mfma_f32_16x16x32_bf16 v[48:51], v[140:143], v[190:193], v[48:51]
	v_mfma_f32_16x16x32_bf16 v[40:43], v[158:161], v[190:193], v[40:43]
	v_mfma_f32_16x16x32_bf16 v[32:35], v[140:143], v[198:201], v[32:35]
	v_mfma_f32_16x16x32_bf16 v[24:27], v[158:161], v[198:201], v[24:27]
	v_mfma_f32_16x16x32_bf16 v[16:19], v[140:143], v[206:209], v[16:19]
	v_mfma_f32_16x16x32_bf16 v[8:11], v[158:161], v[206:209], v[8:11]
	v_mfma_f32_16x16x32_bf16 v[60:63], v[154:157], v[186:189], v[60:63]
	v_mfma_f32_16x16x32_bf16 v[56:59], v[162:165], v[186:189], v[56:59]
	v_mfma_f32_16x16x32_bf16 v[48:51], v[154:157], v[194:197], v[48:51]
	v_mfma_f32_16x16x32_bf16 v[40:43], v[162:165], v[194:197], v[40:43]
	v_mfma_f32_16x16x32_bf16 v[32:35], v[154:157], v[202:205], v[32:35]
	v_mfma_f32_16x16x32_bf16 v[24:27], v[162:165], v[202:205], v[24:27]
	v_mfma_f32_16x16x32_bf16 v[16:19], v[154:157], v[210:213], v[16:19]
	v_mfma_f32_16x16x32_bf16 v[8:11], v[162:165], v[210:213], v[8:11]
	v_mfma_f32_16x16x32_bf16 v[52:55], v[166:169], v[182:185], v[52:55]
	v_mfma_f32_16x16x32_bf16 v[44:47], v[174:177], v[182:185], v[44:47]
	v_mfma_f32_16x16x32_bf16 v[36:39], v[166:169], v[190:193], v[36:39]
	v_mfma_f32_16x16x32_bf16 v[28:31], v[174:177], v[190:193], v[28:31]
	v_mfma_f32_16x16x32_bf16 v[20:23], v[166:169], v[198:201], v[20:23]
	v_mfma_f32_16x16x32_bf16 v[12:15], v[174:177], v[198:201], v[12:15]
	v_mfma_f32_16x16x32_bf16 v[4:7], v[166:169], v[206:209], v[4:7]
	v_mfma_f32_16x16x32_bf16 v[0:3], v[174:177], v[206:209], v[0:3]
	v_mfma_f32_16x16x32_bf16 v[52:55], v[170:173], v[186:189], v[52:55]
	v_mfma_f32_16x16x32_bf16 v[44:47], v[178:181], v[186:189], v[44:47]
	v_mfma_f32_16x16x32_bf16 v[36:39], v[170:173], v[194:197], v[36:39]
	v_mfma_f32_16x16x32_bf16 v[28:31], v[178:181], v[194:197], v[28:31]
	v_mfma_f32_16x16x32_bf16 v[20:23], v[170:173], v[202:205], v[20:23]
	v_mfma_f32_16x16x32_bf16 v[12:15], v[178:181], v[202:205], v[12:15]
	v_mfma_f32_16x16x32_bf16 v[4:7], v[170:173], v[210:213], v[4:7]
	v_mfma_f32_16x16x32_bf16 v[0:3], v[178:181], v[210:213], v[0:3]
	s_waitcnt vmcnt(4)
	s_barrier
	ds_read_b128 v[140:143], v151
	ds_read_b128 v[154:157], v151 offset:1024
	ds_read_b128 v[158:161], v151 offset:2048
	ds_read_b128 v[162:165], v151 offset:3072
	ds_read_b128 v[166:169], v152
	ds_read_b128 v[170:173], v152 offset:1024
	ds_read_b128 v[174:177], v152 offset:2048
	ds_read_b128 v[178:181], v152 offset:3072
	s_mov_b32 s98, s40
	s_mov_b32 s99, s41
	s_add_i32 m0, s85, 0
	ds_read_b128 v[182:185], v150 offset:32768
	ds_read_b128 v[186:189], v150 offset:33792
	ds_read_b128 v[190:193], v150 offset:34816
	ds_read_b128 v[194:197], v150 offset:35840
	ds_read_b128 v[198:201], v150 offset:36864
	ds_read_b128 v[202:205], v150 offset:37888
	ds_read_b128 v[206:209], v150 offset:38912
	ds_read_b128 v[210:213], v150 offset:39936
	global_load_lds_dwordx4 v222, s[98:99]
	s_add_u32 s98, s98, 0x20000
	s_addc_u32 s99, s99, 0
	s_add_i32 m0, s85, 0x1000
	s_nop 0
	global_load_lds_dwordx4 v222, s[98:99]
	s_add_u32 s98, s98, 0x20000
	s_addc_u32 s99, s99, 0
	s_add_i32 m0, s85, 0x2000
	s_nop 0
	global_load_lds_dwordx4 v222, s[98:99]
	s_add_u32 s98, s98, 0x20000
	s_addc_u32 s99, s99, 0
	s_add_i32 m0, s85, 0x3000
	s_nop 0
	global_load_lds_dwordx4 v222, s[98:99]
	s_waitcnt vmcnt(8)
	s_waitcnt lgkmcnt(0)
	s_barrier
	s_waitcnt lgkmcnt(0)
	v_mfma_f32_16x16x32_bf16 v[124:127], v[140:143], v[182:185], v[124:127]
	v_mfma_f32_16x16x32_bf16 v[120:123], v[158:161], v[182:185], v[120:123]
	v_mfma_f32_16x16x32_bf16 v[112:115], v[140:143], v[190:193], v[112:115]
	v_mfma_f32_16x16x32_bf16 v[104:107], v[158:161], v[190:193], v[104:107]
	v_mfma_f32_16x16x32_bf16 v[96:99], v[140:143], v[198:201], v[96:99]
	v_mfma_f32_16x16x32_bf16 v[88:91], v[158:161], v[198:201], v[88:91]
	v_mfma_f32_16x16x32_bf16 v[80:83], v[140:143], v[206:209], v[80:83]
	v_mfma_f32_16x16x32_bf16 v[72:75], v[158:161], v[206:209], v[72:75]
	v_mfma_f32_16x16x32_bf16 v[124:127], v[154:157], v[186:189], v[124:127]
	v_mfma_f32_16x16x32_bf16 v[120:123], v[162:165], v[186:189], v[120:123]
	v_mfma_f32_16x16x32_bf16 v[112:115], v[154:157], v[194:197], v[112:115]
	v_mfma_f32_16x16x32_bf16 v[104:107], v[162:165], v[194:197], v[104:107]
	v_mfma_f32_16x16x32_bf16 v[96:99], v[154:157], v[202:205], v[96:99]
	v_mfma_f32_16x16x32_bf16 v[88:91], v[162:165], v[202:205], v[88:91]
	v_mfma_f32_16x16x32_bf16 v[80:83], v[154:157], v[210:213], v[80:83]
	v_mfma_f32_16x16x32_bf16 v[72:75], v[162:165], v[210:213], v[72:75]
	v_mfma_f32_16x16x32_bf16 v[116:119], v[166:169], v[182:185], v[116:119]
	v_mfma_f32_16x16x32_bf16 v[108:111], v[174:177], v[182:185], v[108:111]
	v_mfma_f32_16x16x32_bf16 v[100:103], v[166:169], v[190:193], v[100:103]
	v_mfma_f32_16x16x32_bf16 v[92:95], v[174:177], v[190:193], v[92:95]
	v_mfma_f32_16x16x32_bf16 v[84:87], v[166:169], v[198:201], v[84:87]
	v_mfma_f32_16x16x32_bf16 v[76:79], v[174:177], v[198:201], v[76:79]
	v_mfma_f32_16x16x32_bf16 v[68:71], v[166:169], v[206:209], v[68:71]
	v_mfma_f32_16x16x32_bf16 v[64:67], v[174:177], v[206:209], v[64:67]
	v_mfma_f32_16x16x32_bf16 v[116:119], v[170:173], v[186:189], v[116:119]
	v_mfma_f32_16x16x32_bf16 v[108:111], v[178:181], v[186:189], v[108:111]
	v_mfma_f32_16x16x32_bf16 v[100:103], v[170:173], v[194:197], v[100:103]
	v_mfma_f32_16x16x32_bf16 v[92:95], v[178:181], v[194:197], v[92:95]
	v_mfma_f32_16x16x32_bf16 v[84:87], v[170:173], v[202:205], v[84:87]
	v_mfma_f32_16x16x32_bf16 v[76:79], v[178:181], v[202:205], v[76:79]
	v_mfma_f32_16x16x32_bf16 v[68:71], v[170:173], v[210:213], v[68:71]
	v_mfma_f32_16x16x32_bf16 v[64:67], v[178:181], v[210:213], v[64:67]
	s_barrier
	s_add_i32 s40, s61, s5
	v_lshl_add_u64 v[144:145], v[144:145], 0, s[12:13]
	s_mov_b32 m0, s40
	ds_read_b128 v[182:185], v150 offset:49152
	ds_read_b128 v[186:189], v150 offset:50176
	ds_read_b128 v[190:193], v150 offset:51200
	ds_read_b128 v[194:197], v150 offset:52224
	ds_read_b128 v[198:201], v150 offset:53248
	ds_read_b128 v[202:205], v150 offset:54272
	ds_read_b128 v[206:209], v150 offset:55296
	ds_read_b128 v[210:213], v150 offset:56320
	global_load_lds_dwordx4 v[144:145], off
	s_add_i32 m0, s40, 0x2000
	s_add_u32 s38, s38, 0x80080
	v_lshl_add_u64 v[144:145], v[214:215], 0, s[12:13]
	s_addc_u32 s39, s39, 0
	s_add_i32 s40, s62, s5
	global_load_lds_dwordx4 v[144:145], off
	v_lshl_add_u64 v[144:145], s[38:39], 0, v[130:131]
	s_mov_b32 m0, s40
	s_nop 0
	global_load_lds_dwordx4 v[144:145], off
	v_lshl_add_u64 v[144:145], s[38:39], 0, v[134:135]
	s_add_i32 m0, s40, 0x2000
	s_nop 0
	global_load_lds_dwordx4 v[144:145], off
	s_waitcnt vmcnt(8)
	s_waitcnt lgkmcnt(0)
	s_barrier
	s_waitcnt lgkmcnt(0)
	v_mfma_f32_16x16x32_bf16 v[60:63], v[140:143], v[182:185], v[60:63]
	v_mfma_f32_16x16x32_bf16 v[56:59], v[158:161], v[182:185], v[56:59]
	v_mfma_f32_16x16x32_bf16 v[48:51], v[140:143], v[190:193], v[48:51]
	v_mfma_f32_16x16x32_bf16 v[40:43], v[158:161], v[190:193], v[40:43]
	v_mfma_f32_16x16x32_bf16 v[32:35], v[140:143], v[198:201], v[32:35]
	v_mfma_f32_16x16x32_bf16 v[24:27], v[158:161], v[198:201], v[24:27]
	v_mfma_f32_16x16x32_bf16 v[16:19], v[140:143], v[206:209], v[16:19]
	v_mfma_f32_16x16x32_bf16 v[8:11], v[158:161], v[206:209], v[8:11]
	v_mfma_f32_16x16x32_bf16 v[60:63], v[154:157], v[186:189], v[60:63]
	v_mfma_f32_16x16x32_bf16 v[56:59], v[162:165], v[186:189], v[56:59]
	v_mfma_f32_16x16x32_bf16 v[48:51], v[154:157], v[194:197], v[48:51]
	v_mfma_f32_16x16x32_bf16 v[40:43], v[162:165], v[194:197], v[40:43]
	v_mfma_f32_16x16x32_bf16 v[32:35], v[154:157], v[202:205], v[32:35]
	v_mfma_f32_16x16x32_bf16 v[24:27], v[162:165], v[202:205], v[24:27]
	v_mfma_f32_16x16x32_bf16 v[16:19], v[154:157], v[210:213], v[16:19]
	v_mfma_f32_16x16x32_bf16 v[8:11], v[162:165], v[210:213], v[8:11]
	v_mfma_f32_16x16x32_bf16 v[52:55], v[166:169], v[182:185], v[52:55]
	v_mfma_f32_16x16x32_bf16 v[44:47], v[174:177], v[182:185], v[44:47]
	v_mfma_f32_16x16x32_bf16 v[36:39], v[166:169], v[190:193], v[36:39]
	v_mfma_f32_16x16x32_bf16 v[28:31], v[174:177], v[190:193], v[28:31]
	v_mfma_f32_16x16x32_bf16 v[20:23], v[166:169], v[198:201], v[20:23]
	v_mfma_f32_16x16x32_bf16 v[12:15], v[174:177], v[198:201], v[12:15]
	v_mfma_f32_16x16x32_bf16 v[4:7], v[166:169], v[206:209], v[4:7]
	v_mfma_f32_16x16x32_bf16 v[0:3], v[174:177], v[206:209], v[0:3]
	v_mfma_f32_16x16x32_bf16 v[52:55], v[170:173], v[186:189], v[52:55]
	v_mfma_f32_16x16x32_bf16 v[44:47], v[178:181], v[186:189], v[44:47]
	v_mfma_f32_16x16x32_bf16 v[36:39], v[170:173], v[194:197], v[36:39]
	v_mfma_f32_16x16x32_bf16 v[28:31], v[178:181], v[194:197], v[28:31]
	v_mfma_f32_16x16x32_bf16 v[20:23], v[170:173], v[202:205], v[20:23]
	v_mfma_f32_16x16x32_bf16 v[12:15], v[178:181], v[202:205], v[12:15]
	v_mfma_f32_16x16x32_bf16 v[4:7], v[170:173], v[210:213], v[4:7]
	v_mfma_f32_16x16x32_bf16 v[0:3], v[178:181], v[210:213], v[0:3]
	s_add_i32 s75, s75, 2
	s_add_u32 s36, s36, 0x100
	s_addc_u32 s37, s37, 0
	s_add_u32 s73, s73, 0x100
	s_addc_u32 s74, s74, 0
	s_cmp_gt_u32 s75, 29
	s_waitcnt vmcnt(4)
	s_barrier
	s_cbranch_scc0 .LBB0_785
	s_setprio 0
	s_and_b64 vcc, exec, s[14:15]
	s_cbranch_vccz .LBB0_788
	s_barrier

.Lprio_skip7:
.LBB0_1084:
	ds_read_b128 v[140:143], v150
	ds_read_b128 v[144:147], v150 offset:1024
	ds_read_b128 v[156:159], v150 offset:2048
	ds_read_b128 v[160:163], v150 offset:3072
	ds_read_b128 v[164:167], v151
	ds_read_b128 v[168:171], v151 offset:1024
	ds_read_b128 v[172:175], v151 offset:2048
	ds_read_b128 v[176:179], v151 offset:3072
	s_add_u32 s36, s0, 0xfff80080
	s_addc_u32 s37, s1, -1
	s_cmp_eq_u32 s74, 28
	s_cselect_b32 s39, s68, s37
	s_cselect_b32 s38, s69, s36
	s_cselect_b32 s37, s70, s73
	s_cselect_b32 s36, s71, s72
	s_sub_u32 s98, s0, 0x80000
	s_subb_u32 s99, s1, 0
	s_add_i32 m0, s85, 0x8000
	ds_read_b128 v[180:183], v152
	ds_read_b128 v[184:187], v152 offset:1024
	ds_read_b128 v[188:191], v152 offset:2048
	ds_read_b128 v[192:195], v152 offset:3072
	ds_read_b128 v[196:199], v152 offset:4096
	ds_read_b128 v[200:203], v152 offset:5120
	ds_read_b128 v[204:207], v152 offset:6144
	ds_read_b128 v[208:211], v152 offset:7168
	global_load_lds_dwordx4 v222, s[98:99]
	s_add_u32 s98, s98, 0x20000
	s_addc_u32 s99, s99, 0
	s_add_i32 m0, s85, 0x9000
	s_nop 0
	global_load_lds_dwordx4 v222, s[98:99]
	s_add_u32 s98, s98, 0x20000
	s_addc_u32 s99, s99, 0
	s_add_i32 m0, s85, 0xa000
	s_nop 0
	global_load_lds_dwordx4 v222, s[98:99]
	s_add_u32 s98, s98, 0x20000
	s_addc_u32 s99, s99, 0
	s_add_i32 m0, s85, 0xb000
	s_nop 0
	global_load_lds_dwordx4 v222, s[98:99]
	s_waitcnt vmcnt(8)
	s_waitcnt lgkmcnt(0)
	s_barrier
	s_waitcnt lgkmcnt(0)
	v_mfma_f32_16x16x32_bf16 v[124:127], v[140:143], v[180:183], v[124:127]
	v_mfma_f32_16x16x32_bf16 v[120:123], v[156:159], v[180:183], v[120:123]
	v_mfma_f32_16x16x32_bf16 v[108:111], v[140:143], v[188:191], v[108:111]
	v_mfma_f32_16x16x32_bf16 v[104:107], v[156:159], v[188:191], v[104:107]
	v_mfma_f32_16x16x32_bf16 v[92:95], v[140:143], v[196:199], v[92:95]
	v_mfma_f32_16x16x32_bf16 v[88:91], v[156:159], v[196:199], v[88:91]
	v_mfma_f32_16x16x32_bf16 v[76:79], v[140:143], v[204:207], v[76:79]
	v_mfma_f32_16x16x32_bf16 v[72:75], v[156:159], v[204:207], v[72:75]
	v_mfma_f32_16x16x32_bf16 v[124:127], v[144:147], v[184:187], v[124:127]
	v_mfma_f32_16x16x32_bf16 v[120:123], v[160:163], v[184:187], v[120:123]
	v_mfma_f32_16x16x32_bf16 v[108:111], v[144:147], v[192:195], v[108:111]
	v_mfma_f32_16x16x32_bf16 v[104:107], v[160:163], v[192:195], v[104:107]
	v_mfma_f32_16x16x32_bf16 v[92:95], v[144:147], v[200:203], v[92:95]
	v_mfma_f32_16x16x32_bf16 v[88:91], v[160:163], v[200:203], v[88:91]
	v_mfma_f32_16x16x32_bf16 v[76:79], v[144:147], v[208:211], v[76:79]
	v_mfma_f32_16x16x32_bf16 v[72:75], v[160:163], v[208:211], v[72:75]
	v_mfma_f32_16x16x32_bf16 v[116:119], v[164:167], v[180:183], v[116:119]
	v_mfma_f32_16x16x32_bf16 v[112:115], v[172:175], v[180:183], v[112:115]
	v_mfma_f32_16x16x32_bf16 v[100:103], v[164:167], v[188:191], v[100:103]
	v_mfma_f32_16x16x32_bf16 v[96:99], v[172:175], v[188:191], v[96:99]
	v_mfma_f32_16x16x32_bf16 v[84:87], v[164:167], v[196:199], v[84:87]
	v_mfma_f32_16x16x32_bf16 v[80:83], v[172:175], v[196:199], v[80:83]
	v_mfma_f32_16x16x32_bf16 v[68:71], v[164:167], v[204:207], v[68:71]
	v_mfma_f32_16x16x32_bf16 v[64:67], v[172:175], v[204:207], v[64:67]
	v_mfma_f32_16x16x32_bf16 v[116:119], v[168:171], v[184:187], v[116:119]
	v_mfma_f32_16x16x32_bf16 v[112:115], v[176:179], v[184:187], v[112:115]
	v_mfma_f32_16x16x32_bf16 v[100:103], v[168:171], v[192:195], v[100:103]
	v_mfma_f32_16x16x32_bf16 v[96:99], v[176:179], v[192:195], v[96:99]
	v_mfma_f32_16x16x32_bf16 v[84:87], v[168:171], v[200:203], v[84:87]
	v_mfma_f32_16x16x32_bf16 v[80:83], v[176:179], v[200:203], v[80:83]
	v_mfma_f32_16x16x32_bf16 v[68:71], v[168:171], v[208:211], v[68:71]
	v_mfma_f32_16x16x32_bf16 v[64:67], v[176:179], v[208:211], v[64:67]
	s_barrier
	s_add_i32 s75, s56, s5
	v_lshl_add_u64 v[212:213], s[36:37], 0, v[130:131]
	s_mov_b32 m0, s75
	ds_read_b128 v[180:183], v152 offset:16384
	ds_read_b128 v[184:187], v152 offset:17408
	ds_read_b128 v[188:191], v152 offset:18432
	ds_read_b128 v[192:195], v152 offset:19456
	ds_read_b128 v[196:199], v152 offset:20480
	ds_read_b128 v[200:203], v152 offset:21504
	ds_read_b128 v[204:207], v152 offset:22528
	ds_read_b128 v[208:211], v152 offset:23552
	global_load_lds_dwordx4 v[212:213], off
	s_add_i32 m0, s75, 0x2000
	s_add_u32 s76, s36, 0x80000
	v_lshl_add_u64 v[214:215], s[36:37], 0, v[134:135]
	s_addc_u32 s77, s37, 0
	s_add_i32 s75, s57, s5
	global_load_lds_dwordx4 v[214:215], off
	v_lshl_add_u64 v[216:217], s[76:77], 0, v[130:131]
	s_mov_b32 m0, s75
	global_load_lds_dwordx4 v[216:217], off
	v_lshl_add_u64 v[216:217], s[76:77], 0, v[134:135]
	s_add_i32 m0, s75, 0x2000
	s_nop 0
	global_load_lds_dwordx4 v[216:217], off
	s_waitcnt vmcnt(8)
	s_waitcnt lgkmcnt(0)
	s_barrier
	s_waitcnt lgkmcnt(0)
	v_mfma_f32_16x16x32_bf16 v[60:63], v[140:143], v[180:183], v[60:63]
	v_mfma_f32_16x16x32_bf16 v[56:59], v[156:159], v[180:183], v[56:59]
	v_mfma_f32_16x16x32_bf16 v[44:47], v[140:143], v[188:191], v[44:47]
	v_mfma_f32_16x16x32_bf16 v[40:43], v[156:159], v[188:191], v[40:43]
	v_mfma_f32_16x16x32_bf16 v[28:31], v[140:143], v[196:199], v[28:31]
	v_mfma_f32_16x16x32_bf16 v[24:27], v[156:159], v[196:199], v[24:27]
	v_mfma_f32_16x16x32_bf16 v[12:15], v[140:143], v[204:207], v[12:15]
	v_mfma_f32_16x16x32_bf16 v[8:11], v[156:159], v[204:207], v[8:11]
	v_mfma_f32_16x16x32_bf16 v[60:63], v[144:147], v[184:187], v[60:63]
	v_mfma_f32_16x16x32_bf16 v[56:59], v[160:163], v[184:187], v[56:59]
	v_mfma_f32_16x16x32_bf16 v[44:47], v[144:147], v[192:195], v[44:47]
	v_mfma_f32_16x16x32_bf16 v[40:43], v[160:163], v[192:195], v[40:43]
	v_mfma_f32_16x16x32_bf16 v[28:31], v[144:147], v[200:203], v[28:31]
	v_mfma_f32_16x16x32_bf16 v[24:27], v[160:163], v[200:203], v[24:27]
	v_mfma_f32_16x16x32_bf16 v[12:15], v[144:147], v[208:211], v[12:15]
	v_mfma_f32_16x16x32_bf16 v[8:11], v[160:163], v[208:211], v[8:11]
	v_mfma_f32_16x16x32_bf16 v[52:55], v[164:167], v[180:183], v[52:55]
	v_mfma_f32_16x16x32_bf16 v[48:51], v[172:175], v[180:183], v[48:51]
	v_mfma_f32_16x16x32_bf16 v[36:39], v[164:167], v[188:191], v[36:39]
	v_mfma_f32_16x16x32_bf16 v[32:35], v[172:175], v[188:191], v[32:35]
	v_mfma_f32_16x16x32_bf16 v[20:23], v[164:167], v[196:199], v[20:23]
	v_mfma_f32_16x16x32_bf16 v[16:19], v[172:175], v[196:199], v[16:19]
	v_mfma_f32_16x16x32_bf16 v[4:7], v[164:167], v[204:207], v[4:7]
	v_mfma_f32_16x16x32_bf16 v[0:3], v[172:175], v[204:207], v[0:3]
	v_mfma_f32_16x16x32_bf16 v[52:55], v[168:171], v[184:187], v[52:55]
	v_mfma_f32_16x16x32_bf16 v[48:51], v[176:179], v[184:187], v[48:51]
	v_mfma_f32_16x16x32_bf16 v[36:39], v[168:171], v[192:195], v[36:39]
	v_mfma_f32_16x16x32_bf16 v[32:35], v[176:179], v[192:195], v[32:35]
	v_mfma_f32_16x16x32_bf16 v[20:23], v[168:171], v[200:203], v[20:23]
	v_mfma_f32_16x16x32_bf16 v[16:19], v[176:179], v[200:203], v[16:19]
	v_mfma_f32_16x16x32_bf16 v[4:7], v[168:171], v[208:211], v[4:7]
	v_mfma_f32_16x16x32_bf16 v[0:3], v[176:179], v[208:211], v[0:3]
	s_waitcnt vmcnt(4)
	s_barrier
	ds_read_b128 v[140:143], v153
	ds_read_b128 v[144:147], v153 offset:1024
	ds_read_b128 v[156:159], v153 offset:2048
	ds_read_b128 v[160:163], v153 offset:3072
	ds_read_b128 v[164:167], v154
	ds_read_b128 v[168:171], v154 offset:1024
	ds_read_b128 v[172:175], v154 offset:2048
	ds_read_b128 v[176:179], v154 offset:3072
	s_mov_b32 s98, s38
	s_mov_b32 s99, s39
	s_add_i32 m0, s85, 0
	ds_read_b128 v[180:183], v152 offset:32768
	ds_read_b128 v[184:187], v152 offset:33792
	ds_read_b128 v[188:191], v152 offset:34816
	ds_read_b128 v[192:195], v152 offset:35840
	ds_read_b128 v[196:199], v152 offset:36864
	ds_read_b128 v[200:203], v152 offset:37888
	ds_read_b128 v[204:207], v152 offset:38912
	ds_read_b128 v[208:211], v152 offset:39936
	global_load_lds_dwordx4 v222, s[98:99]
	s_add_u32 s98, s98, 0x20000
	s_addc_u32 s99, s99, 0
	s_add_i32 m0, s85, 0x1000
	s_nop 0
	global_load_lds_dwordx4 v222, s[98:99]
	s_add_u32 s98, s98, 0x20000
	s_addc_u32 s99, s99, 0
	s_add_i32 m0, s85, 0x2000
	s_nop 0
	global_load_lds_dwordx4 v222, s[98:99]
	s_add_u32 s98, s98, 0x20000
	s_addc_u32 s99, s99, 0
	s_add_i32 m0, s85, 0x3000
	s_nop 0
	global_load_lds_dwordx4 v222, s[98:99]
	s_waitcnt vmcnt(8)
	s_waitcnt lgkmcnt(0)
	s_barrier
	s_waitcnt lgkmcnt(0)
	v_mfma_f32_16x16x32_bf16 v[124:127], v[140:143], v[180:183], v[124:127]
	v_mfma_f32_16x16x32_bf16 v[120:123], v[156:159], v[180:183], v[120:123]
	v_mfma_f32_16x16x32_bf16 v[108:111], v[140:143], v[188:191], v[108:111]
	v_mfma_f32_16x16x32_bf16 v[104:107], v[156:159], v[188:191], v[104:107]
	v_mfma_f32_16x16x32_bf16 v[92:95], v[140:143], v[196:199], v[92:95]
	v_mfma_f32_16x16x32_bf16 v[88:91], v[156:159], v[196:199], v[88:91]
	v_mfma_f32_16x16x32_bf16 v[76:79], v[140:143], v[204:207], v[76:79]
	v_mfma_f32_16x16x32_bf16 v[72:75], v[156:159], v[204:207], v[72:75]
	v_mfma_f32_16x16x32_bf16 v[124:127], v[144:147], v[184:187], v[124:127]
	v_mfma_f32_16x16x32_bf16 v[120:123], v[160:163], v[184:187], v[120:123]
	v_mfma_f32_16x16x32_bf16 v[108:111], v[144:147], v[192:195], v[108:111]
	v_mfma_f32_16x16x32_bf16 v[104:107], v[160:163], v[192:195], v[104:107]
	v_mfma_f32_16x16x32_bf16 v[92:95], v[144:147], v[200:203], v[92:95]
	v_mfma_f32_16x16x32_bf16 v[88:91], v[160:163], v[200:203], v[88:91]
	v_mfma_f32_16x16x32_bf16 v[76:79], v[144:147], v[208:211], v[76:79]
	v_mfma_f32_16x16x32_bf16 v[72:75], v[160:163], v[208:211], v[72:75]
	v_mfma_f32_16x16x32_bf16 v[116:119], v[164:167], v[180:183], v[116:119]
	v_mfma_f32_16x16x32_bf16 v[112:115], v[172:175], v[180:183], v[112:115]
	v_mfma_f32_16x16x32_bf16 v[100:103], v[164:167], v[188:191], v[100:103]
	v_mfma_f32_16x16x32_bf16 v[96:99], v[172:175], v[188:191], v[96:99]
	v_mfma_f32_16x16x32_bf16 v[84:87], v[164:167], v[196:199], v[84:87]
	v_mfma_f32_16x16x32_bf16 v[80:83], v[172:175], v[196:199], v[80:83]
	v_mfma_f32_16x16x32_bf16 v[68:71], v[164:167], v[204:207], v[68:71]
	v_mfma_f32_16x16x32_bf16 v[64:67], v[172:175], v[204:207], v[64:67]
	v_mfma_f32_16x16x32_bf16 v[116:119], v[168:171], v[184:187], v[116:119]
	v_mfma_f32_16x16x32_bf16 v[112:115], v[176:179], v[184:187], v[112:115]
	v_mfma_f32_16x16x32_bf16 v[100:103], v[168:171], v[192:195], v[100:103]
	v_mfma_f32_16x16x32_bf16 v[96:99], v[176:179], v[192:195], v[96:99]
	v_mfma_f32_16x16x32_bf16 v[84:87], v[168:171], v[200:203], v[84:87]
	v_mfma_f32_16x16x32_bf16 v[80:83], v[176:179], v[200:203], v[80:83]
	v_mfma_f32_16x16x32_bf16 v[68:71], v[168:171], v[208:211], v[68:71]
	v_mfma_f32_16x16x32_bf16 v[64:67], v[176:179], v[208:211], v[64:67]
	s_barrier
	s_add_i32 s38, s58, s5
	v_lshl_add_u64 v[212:213], v[212:213], 0, s[14:15]
	s_mov_b32 m0, s38
	ds_read_b128 v[180:183], v152 offset:49152
	ds_read_b128 v[184:187], v152 offset:50176
	ds_read_b128 v[188:191], v152 offset:51200
	ds_read_b128 v[192:195], v152 offset:52224
	ds_read_b128 v[196:199], v152 offset:53248
	ds_read_b128 v[200:203], v152 offset:54272
	ds_read_b128 v[204:207], v152 offset:55296
	ds_read_b128 v[208:211], v152 offset:56320
	global_load_lds_dwordx4 v[212:213], off
	s_add_i32 m0, s38, 0x2000
	s_add_u32 s36, s36, 0x80080
	v_lshl_add_u64 v[212:213], v[214:215], 0, s[14:15]
	s_addc_u32 s37, s37, 0
	s_add_i32 s38, s59, s5
	global_load_lds_dwordx4 v[212:213], off
	v_lshl_add_u64 v[212:213], s[36:37], 0, v[130:131]
	s_mov_b32 m0, s38
	s_nop 0
	global_load_lds_dwordx4 v[212:213], off
	v_lshl_add_u64 v[212:213], s[36:37], 0, v[134:135]
	s_add_i32 m0, s38, 0x2000
	s_nop 0
	global_load_lds_dwordx4 v[212:213], off
	s_waitcnt vmcnt(8)
	s_waitcnt lgkmcnt(0)
	s_barrier
	s_waitcnt lgkmcnt(0)
	v_mfma_f32_16x16x32_bf16 v[60:63], v[140:143], v[180:183], v[60:63]
	v_mfma_f32_16x16x32_bf16 v[56:59], v[156:159], v[180:183], v[56:59]
	v_mfma_f32_16x16x32_bf16 v[44:47], v[140:143], v[188:191], v[44:47]
	v_mfma_f32_16x16x32_bf16 v[40:43], v[156:159], v[188:191], v[40:43]
	v_mfma_f32_16x16x32_bf16 v[28:31], v[140:143], v[196:199], v[28:31]
	v_mfma_f32_16x16x32_bf16 v[24:27], v[156:159], v[196:199], v[24:27]
	v_mfma_f32_16x16x32_bf16 v[12:15], v[140:143], v[204:207], v[12:15]
	v_mfma_f32_16x16x32_bf16 v[8:11], v[156:159], v[204:207], v[8:11]
	v_mfma_f32_16x16x32_bf16 v[60:63], v[144:147], v[184:187], v[60:63]
	v_mfma_f32_16x16x32_bf16 v[56:59], v[160:163], v[184:187], v[56:59]
	v_mfma_f32_16x16x32_bf16 v[44:47], v[144:147], v[192:195], v[44:47]
	v_mfma_f32_16x16x32_bf16 v[40:43], v[160:163], v[192:195], v[40:43]
	v_mfma_f32_16x16x32_bf16 v[28:31], v[144:147], v[200:203], v[28:31]
	v_mfma_f32_16x16x32_bf16 v[24:27], v[160:163], v[200:203], v[24:27]
	v_mfma_f32_16x16x32_bf16 v[12:15], v[144:147], v[208:211], v[12:15]
	v_mfma_f32_16x16x32_bf16 v[8:11], v[160:163], v[208:211], v[8:11]
	v_mfma_f32_16x16x32_bf16 v[52:55], v[164:167], v[180:183], v[52:55]
	v_mfma_f32_16x16x32_bf16 v[48:51], v[172:175], v[180:183], v[48:51]
	v_mfma_f32_16x16x32_bf16 v[36:39], v[164:167], v[188:191], v[36:39]
	v_mfma_f32_16x16x32_bf16 v[32:35], v[172:175], v[188:191], v[32:35]
	v_mfma_f32_16x16x32_bf16 v[20:23], v[164:167], v[196:199], v[20:23]
	v_mfma_f32_16x16x32_bf16 v[16:19], v[172:175], v[196:199], v[16:19]
	v_mfma_f32_16x16x32_bf16 v[4:7], v[164:167], v[204:207], v[4:7]
	v_mfma_f32_16x16x32_bf16 v[0:3], v[172:175], v[204:207], v[0:3]
	v_mfma_f32_16x16x32_bf16 v[52:55], v[168:171], v[184:187], v[52:55]
	v_mfma_f32_16x16x32_bf16 v[48:51], v[176:179], v[184:187], v[48:51]
	v_mfma_f32_16x16x32_bf16 v[36:39], v[168:171], v[192:195], v[36:39]
	v_mfma_f32_16x16x32_bf16 v[32:35], v[176:179], v[192:195], v[32:35]
	v_mfma_f32_16x16x32_bf16 v[20:23], v[168:171], v[200:203], v[20:23]
	v_mfma_f32_16x16x32_bf16 v[16:19], v[176:179], v[200:203], v[16:19]
	v_mfma_f32_16x16x32_bf16 v[4:7], v[168:171], v[208:211], v[4:7]
	v_mfma_f32_16x16x32_bf16 v[0:3], v[176:179], v[208:211], v[0:3]
	s_add_i32 s74, s74, 2
	s_add_u32 s0, s0, 0x100
	s_addc_u32 s1, s1, 0
	s_add_u32 s72, s72, 0x100
	s_addc_u32 s73, s73, 0
	s_cmp_gt_u32 s74, 29
	s_waitcnt vmcnt(4)
	s_barrier
	s_cbranch_scc0 .LBB0_1084
	s_setprio 0
	s_and_b64 vcc, exec, s[16:17]
	s_cbranch_vccz .LBB0_1087
	s_barrier

.Lprio_skip8:
.LBB0_1194:
	ds_read_b128 v[120:123], v230
	ds_read_b128 v[132:135], v230 offset:1024
	ds_read_b128 v[136:139], v230 offset:2048
	ds_read_b128 v[140:143], v230 offset:3072
	ds_read_b128 v[144:147], v231
	ds_read_b128 v[148:151], v231 offset:1024
	ds_read_b128 v[152:155], v231 offset:2048
	ds_read_b128 v[156:159], v231 offset:3072
	s_add_u32 s28, s0, s2
	s_addc_u32 s29, s1, s3
	s_cmpk_eq_i32 s2, 0x4000
	s_cselect_b32 s30, 0, s2
	s_cselect_b32 s31, 0, s3
	s_cselect_b32 s28, s57, s28
	s_cselect_b32 s29, s7, s29
	s_add_u32 s30, s10, s30
	s_addc_u32 s31, s11, s31
	s_add_u32 s98, s2, s86
	s_addc_u32 s99, s3, s87
	s_add_i32 m0, s85, 0x8000
	v_lshl_add_u64 v[204:205], v[192:193], 0, s[98:99]
	ds_read_b128 v[160:163], v232
	ds_read_b128 v[164:167], v232 offset:1024
	ds_read_b128 v[168:171], v232 offset:2048
	ds_read_b128 v[172:175], v232 offset:3072
	ds_read_b128 v[176:179], v232 offset:4096
	ds_read_b128 v[180:183], v232 offset:5120
	ds_read_b128 v[196:199], v232 offset:6144
	ds_read_b128 v[200:203], v232 offset:7168
	global_load_lds_dwordx4 v[204:205], off
	s_add_u32 s98, s98, 0x80000
	s_addc_u32 s99, s99, 0
	s_add_i32 m0, s85, 0x9000
	v_lshl_add_u64 v[204:205], v[192:193], 0, s[98:99]
	global_load_lds_dwordx4 v[204:205], off
	s_add_u32 s98, s98, 0x80000
	s_addc_u32 s99, s99, 0
	s_add_i32 m0, s85, 0xa000
	v_lshl_add_u64 v[204:205], v[192:193], 0, s[98:99]
	global_load_lds_dwordx4 v[204:205], off
	s_add_u32 s98, s98, 0x80000
	s_addc_u32 s99, s99, 0
	s_add_i32 m0, s85, 0xb000
	v_lshl_add_u64 v[204:205], v[192:193], 0, s[98:99]
	global_load_lds_dwordx4 v[204:205], off
	s_waitcnt vmcnt(8)
	s_waitcnt lgkmcnt(0)
	s_barrier
	s_waitcnt lgkmcnt(0)
	v_mfma_f32_16x16x32_bf16 v[128:131], v[120:123], v[160:163], v[128:131]
	v_mfma_f32_16x16x32_bf16 v[124:127], v[136:139], v[160:163], v[124:127]
	v_mfma_f32_16x16x32_bf16 v[108:111], v[120:123], v[168:171], v[108:111]
	v_mfma_f32_16x16x32_bf16 v[104:107], v[136:139], v[168:171], v[104:107]
	v_mfma_f32_16x16x32_bf16 v[92:95], v[120:123], v[176:179], v[92:95]
	v_mfma_f32_16x16x32_bf16 v[88:91], v[136:139], v[176:179], v[88:91]
	v_mfma_f32_16x16x32_bf16 v[76:79], v[120:123], v[196:199], v[76:79]
	v_mfma_f32_16x16x32_bf16 v[72:75], v[136:139], v[196:199], v[72:75]
	v_mfma_f32_16x16x32_bf16 v[128:131], v[132:135], v[164:167], v[128:131]
	v_mfma_f32_16x16x32_bf16 v[124:127], v[140:143], v[164:167], v[124:127]
	v_mfma_f32_16x16x32_bf16 v[108:111], v[132:135], v[172:175], v[108:111]
	v_mfma_f32_16x16x32_bf16 v[104:107], v[140:143], v[172:175], v[104:107]
	v_mfma_f32_16x16x32_bf16 v[92:95], v[132:135], v[180:183], v[92:95]
	v_mfma_f32_16x16x32_bf16 v[88:91], v[140:143], v[180:183], v[88:91]
	v_mfma_f32_16x16x32_bf16 v[76:79], v[132:135], v[200:203], v[76:79]
	v_mfma_f32_16x16x32_bf16 v[72:75], v[140:143], v[200:203], v[72:75]
	v_mfma_f32_16x16x32_bf16 v[116:119], v[144:147], v[160:163], v[116:119]
	v_mfma_f32_16x16x32_bf16 v[112:115], v[152:155], v[160:163], v[112:115]
	v_mfma_f32_16x16x32_bf16 v[100:103], v[144:147], v[168:171], v[100:103]
	v_mfma_f32_16x16x32_bf16 v[96:99], v[152:155], v[168:171], v[96:99]
	v_mfma_f32_16x16x32_bf16 v[84:87], v[144:147], v[176:179], v[84:87]
	v_mfma_f32_16x16x32_bf16 v[80:83], v[152:155], v[176:179], v[80:83]
	v_mfma_f32_16x16x32_bf16 v[68:71], v[144:147], v[196:199], v[68:71]
	v_mfma_f32_16x16x32_bf16 v[64:67], v[152:155], v[196:199], v[64:67]
	v_mfma_f32_16x16x32_bf16 v[116:119], v[148:151], v[164:167], v[116:119]
	v_mfma_f32_16x16x32_bf16 v[112:115], v[156:159], v[164:167], v[112:115]
	v_mfma_f32_16x16x32_bf16 v[100:103], v[148:151], v[172:175], v[100:103]
	v_mfma_f32_16x16x32_bf16 v[96:99], v[156:159], v[172:175], v[96:99]
	v_mfma_f32_16x16x32_bf16 v[84:87], v[148:151], v[180:183], v[84:87]
	v_mfma_f32_16x16x32_bf16 v[80:83], v[156:159], v[180:183], v[80:83]
	v_mfma_f32_16x16x32_bf16 v[68:71], v[148:151], v[200:203], v[68:71]
	v_mfma_f32_16x16x32_bf16 v[64:67], v[156:159], v[200:203], v[64:67]
	s_barrier
	s_mov_b32 m0, s50
	v_lshl_add_u64 v[204:205], s[28:29], 0, v[188:189]
	s_add_u32 s60, s28, 0x200000
	ds_read_b128 v[160:163], v232 offset:16384
	ds_read_b128 v[164:167], v232 offset:17408
	ds_read_b128 v[168:171], v232 offset:18432
	ds_read_b128 v[172:175], v232 offset:19456
	ds_read_b128 v[176:179], v232 offset:20480
	ds_read_b128 v[180:183], v232 offset:21504
	ds_read_b128 v[196:199], v232 offset:22528
	ds_read_b128 v[200:203], v232 offset:23552
	global_load_lds_dwordx4 v[204:205], off
	v_lshl_add_u64 v[206:207], s[28:29], 0, v[184:185]
	s_mov_b32 m0, s51
	s_addc_u32 s61, s29, 0
	global_load_lds_dwordx4 v[206:207], off
	v_lshl_add_u64 v[208:209], s[60:61], 0, v[188:189]
	s_mov_b32 m0, s52
	global_load_lds_dwordx4 v[208:209], off
	v_lshl_add_u64 v[208:209], s[60:61], 0, v[184:185]
	s_mov_b32 m0, s53
	s_nop 0
	global_load_lds_dwordx4 v[208:209], off
	s_waitcnt vmcnt(8)
	s_waitcnt lgkmcnt(0)
	s_barrier
	s_waitcnt lgkmcnt(0)
	v_mfma_f32_16x16x32_bf16 v[60:63], v[120:123], v[160:163], v[60:63]
	v_mfma_f32_16x16x32_bf16 v[56:59], v[136:139], v[160:163], v[56:59]
	v_mfma_f32_16x16x32_bf16 v[44:47], v[120:123], v[168:171], v[44:47]
	v_mfma_f32_16x16x32_bf16 v[40:43], v[136:139], v[168:171], v[40:43]
	v_mfma_f32_16x16x32_bf16 v[28:31], v[120:123], v[176:179], v[28:31]
	v_mfma_f32_16x16x32_bf16 v[24:27], v[136:139], v[176:179], v[24:27]
	v_mfma_f32_16x16x32_bf16 v[12:15], v[120:123], v[196:199], v[12:15]
	v_mfma_f32_16x16x32_bf16 v[8:11], v[136:139], v[196:199], v[8:11]
	v_mfma_f32_16x16x32_bf16 v[60:63], v[132:135], v[164:167], v[60:63]
	v_mfma_f32_16x16x32_bf16 v[56:59], v[140:143], v[164:167], v[56:59]
	v_mfma_f32_16x16x32_bf16 v[44:47], v[132:135], v[172:175], v[44:47]
	v_mfma_f32_16x16x32_bf16 v[40:43], v[140:143], v[172:175], v[40:43]
	v_mfma_f32_16x16x32_bf16 v[28:31], v[132:135], v[180:183], v[28:31]
	v_mfma_f32_16x16x32_bf16 v[24:27], v[140:143], v[180:183], v[24:27]
	v_mfma_f32_16x16x32_bf16 v[12:15], v[132:135], v[200:203], v[12:15]
	v_mfma_f32_16x16x32_bf16 v[8:11], v[140:143], v[200:203], v[8:11]
	v_mfma_f32_16x16x32_bf16 v[52:55], v[144:147], v[160:163], v[52:55]
	v_mfma_f32_16x16x32_bf16 v[48:51], v[152:155], v[160:163], v[48:51]
	v_mfma_f32_16x16x32_bf16 v[36:39], v[144:147], v[168:171], v[36:39]
	v_mfma_f32_16x16x32_bf16 v[32:35], v[152:155], v[168:171], v[32:35]
	v_mfma_f32_16x16x32_bf16 v[20:23], v[144:147], v[176:179], v[20:23]
	v_mfma_f32_16x16x32_bf16 v[16:19], v[152:155], v[176:179], v[16:19]
	v_mfma_f32_16x16x32_bf16 v[4:7], v[144:147], v[196:199], v[4:7]
	v_mfma_f32_16x16x32_bf16 v[0:3], v[152:155], v[196:199], v[0:3]
	v_mfma_f32_16x16x32_bf16 v[52:55], v[148:151], v[164:167], v[52:55]
	v_mfma_f32_16x16x32_bf16 v[48:51], v[156:159], v[164:167], v[48:51]
	v_mfma_f32_16x16x32_bf16 v[36:39], v[148:151], v[172:175], v[36:39]
	v_mfma_f32_16x16x32_bf16 v[32:35], v[156:159], v[172:175], v[32:35]
	v_mfma_f32_16x16x32_bf16 v[20:23], v[148:151], v[180:183], v[20:23]
	v_mfma_f32_16x16x32_bf16 v[16:19], v[156:159], v[180:183], v[16:19]
	v_mfma_f32_16x16x32_bf16 v[4:7], v[148:151], v[200:203], v[4:7]
	v_mfma_f32_16x16x32_bf16 v[0:3], v[156:159], v[200:203], v[0:3]
	s_waitcnt vmcnt(4)
	s_barrier
	ds_read_b128 v[120:123], v234
	ds_read_b128 v[132:135], v234 offset:1024
	ds_read_b128 v[136:139], v234 offset:2048
	ds_read_b128 v[140:143], v234 offset:3072
	ds_read_b128 v[144:147], v235
	ds_read_b128 v[148:151], v235 offset:1024
	ds_read_b128 v[152:155], v235 offset:2048
	ds_read_b128 v[156:159], v235 offset:3072
	s_add_u32 s98, s30, s96
	s_addc_u32 s99, s31, s97
	s_add_i32 m0, s85, 0
	v_lshl_add_u64 v[212:213], s[98:99], 0, v[190:191]
	ds_read_b128 v[160:163], v232 offset:32768
	ds_read_b128 v[164:167], v232 offset:33792
	ds_read_b128 v[168:171], v232 offset:34816
	ds_read_b128 v[172:175], v232 offset:35840
	ds_read_b128 v[176:179], v232 offset:36864
	ds_read_b128 v[180:183], v232 offset:37888
	ds_read_b128 v[196:199], v232 offset:38912
	ds_read_b128 v[200:203], v232 offset:39936
	global_load_lds_dwordx4 v[212:213], off
	s_add_u32 s98, s98, 0x80000
	s_addc_u32 s99, s99, 0
	s_add_i32 m0, s85, 0x1000
	v_lshl_add_u64 v[212:213], s[98:99], 0, v[190:191]
	global_load_lds_dwordx4 v[212:213], off
	s_add_u32 s98, s98, 0x80000
	s_addc_u32 s99, s99, 0
	s_add_i32 m0, s85, 0x2000
	v_lshl_add_u64 v[212:213], s[98:99], 0, v[190:191]
	global_load_lds_dwordx4 v[212:213], off
	s_add_u32 s98, s98, 0x80000
	s_addc_u32 s99, s99, 0
	s_add_i32 m0, s85, 0x3000
	v_lshl_add_u64 v[212:213], s[98:99], 0, v[190:191]
	global_load_lds_dwordx4 v[212:213], off
	s_waitcnt vmcnt(8)
	s_waitcnt lgkmcnt(0)
	s_barrier
	s_waitcnt lgkmcnt(0)
	v_mfma_f32_16x16x32_bf16 v[128:131], v[120:123], v[160:163], v[128:131]
	v_mfma_f32_16x16x32_bf16 v[124:127], v[136:139], v[160:163], v[124:127]
	v_mfma_f32_16x16x32_bf16 v[108:111], v[120:123], v[168:171], v[108:111]
	v_mfma_f32_16x16x32_bf16 v[104:107], v[136:139], v[168:171], v[104:107]
	v_mfma_f32_16x16x32_bf16 v[92:95], v[120:123], v[176:179], v[92:95]
	v_mfma_f32_16x16x32_bf16 v[88:91], v[136:139], v[176:179], v[88:91]
	v_mfma_f32_16x16x32_bf16 v[76:79], v[120:123], v[196:199], v[76:79]
	v_mfma_f32_16x16x32_bf16 v[72:75], v[136:139], v[196:199], v[72:75]
	v_mfma_f32_16x16x32_bf16 v[128:131], v[132:135], v[164:167], v[128:131]
	v_mfma_f32_16x16x32_bf16 v[124:127], v[140:143], v[164:167], v[124:127]
	v_mfma_f32_16x16x32_bf16 v[108:111], v[132:135], v[172:175], v[108:111]
	v_mfma_f32_16x16x32_bf16 v[104:107], v[140:143], v[172:175], v[104:107]
	v_mfma_f32_16x16x32_bf16 v[92:95], v[132:135], v[180:183], v[92:95]
	v_mfma_f32_16x16x32_bf16 v[88:91], v[140:143], v[180:183], v[88:91]
	v_mfma_f32_16x16x32_bf16 v[76:79], v[132:135], v[200:203], v[76:79]
	v_mfma_f32_16x16x32_bf16 v[72:75], v[140:143], v[200:203], v[72:75]
	v_mfma_f32_16x16x32_bf16 v[116:119], v[144:147], v[160:163], v[116:119]
	v_mfma_f32_16x16x32_bf16 v[112:115], v[152:155], v[160:163], v[112:115]
	v_mfma_f32_16x16x32_bf16 v[100:103], v[144:147], v[168:171], v[100:103]
	v_mfma_f32_16x16x32_bf16 v[96:99], v[152:155], v[168:171], v[96:99]
	v_mfma_f32_16x16x32_bf16 v[84:87], v[144:147], v[176:179], v[84:87]
	v_mfma_f32_16x16x32_bf16 v[80:83], v[152:155], v[176:179], v[80:83]
	v_mfma_f32_16x16x32_bf16 v[68:71], v[144:147], v[196:199], v[68:71]
	v_mfma_f32_16x16x32_bf16 v[64:67], v[152:155], v[196:199], v[64:67]
	v_mfma_f32_16x16x32_bf16 v[116:119], v[148:151], v[164:167], v[116:119]
	v_mfma_f32_16x16x32_bf16 v[112:115], v[156:159], v[164:167], v[112:115]
	v_mfma_f32_16x16x32_bf16 v[100:103], v[148:151], v[172:175], v[100:103]
	v_mfma_f32_16x16x32_bf16 v[96:99], v[156:159], v[172:175], v[96:99]
	v_mfma_f32_16x16x32_bf16 v[84:87], v[148:151], v[180:183], v[84:87]
	v_mfma_f32_16x16x32_bf16 v[80:83], v[156:159], v[180:183], v[80:83]
	v_mfma_f32_16x16x32_bf16 v[68:71], v[148:151], v[200:203], v[68:71]
	v_mfma_f32_16x16x32_bf16 v[64:67], v[156:159], v[200:203], v[64:67]
	s_barrier
	s_add_i32 s30, s54, s37
	v_lshl_add_u64 v[204:205], v[204:205], 0, s[18:19]
	s_mov_b32 m0, s30
	ds_read_b128 v[160:163], v232 offset:49152
	ds_read_b128 v[164:167], v232 offset:50176
	ds_read_b128 v[168:171], v232 offset:51200
	ds_read_b128 v[172:175], v232 offset:52224
	ds_read_b128 v[176:179], v232 offset:53248
	ds_read_b128 v[180:183], v232 offset:54272
	ds_read_b128 v[196:199], v232 offset:55296
	ds_read_b128 v[200:203], v232 offset:56320
	global_load_lds_dwordx4 v[204:205], off
	s_add_i32 m0, s30, 0x2000
	s_add_u32 s28, s28, 0x200080
	v_lshl_add_u64 v[204:205], v[206:207], 0, s[18:19]
	s_addc_u32 s29, s29, 0
	s_add_i32 s30, s55, s37
	global_load_lds_dwordx4 v[204:205], off
	v_lshl_add_u64 v[204:205], s[28:29], 0, v[188:189]
	s_mov_b32 m0, s30
	s_nop 0
	global_load_lds_dwordx4 v[204:205], off
	v_lshl_add_u64 v[204:205], s[28:29], 0, v[184:185]
	s_add_i32 m0, s30, 0x2000
	s_nop 0
	global_load_lds_dwordx4 v[204:205], off
	s_waitcnt vmcnt(8)
	s_waitcnt lgkmcnt(0)
	s_barrier
	s_waitcnt lgkmcnt(0)
	v_mfma_f32_16x16x32_bf16 v[60:63], v[120:123], v[160:163], v[60:63]
	v_mfma_f32_16x16x32_bf16 v[56:59], v[136:139], v[160:163], v[56:59]
	v_mfma_f32_16x16x32_bf16 v[44:47], v[120:123], v[168:171], v[44:47]
	v_mfma_f32_16x16x32_bf16 v[40:43], v[136:139], v[168:171], v[40:43]
	v_mfma_f32_16x16x32_bf16 v[28:31], v[120:123], v[176:179], v[28:31]
	v_mfma_f32_16x16x32_bf16 v[24:27], v[136:139], v[176:179], v[24:27]
	v_mfma_f32_16x16x32_bf16 v[12:15], v[120:123], v[196:199], v[12:15]
	v_mfma_f32_16x16x32_bf16 v[8:11], v[136:139], v[196:199], v[8:11]
	v_mfma_f32_16x16x32_bf16 v[60:63], v[132:135], v[164:167], v[60:63]
	v_mfma_f32_16x16x32_bf16 v[56:59], v[140:143], v[164:167], v[56:59]
	v_mfma_f32_16x16x32_bf16 v[44:47], v[132:135], v[172:175], v[44:47]
	v_mfma_f32_16x16x32_bf16 v[40:43], v[140:143], v[172:175], v[40:43]
	v_mfma_f32_16x16x32_bf16 v[28:31], v[132:135], v[180:183], v[28:31]
	v_mfma_f32_16x16x32_bf16 v[24:27], v[140:143], v[180:183], v[24:27]
	v_mfma_f32_16x16x32_bf16 v[12:15], v[132:135], v[200:203], v[12:15]
	v_mfma_f32_16x16x32_bf16 v[8:11], v[140:143], v[200:203], v[8:11]
	v_mfma_f32_16x16x32_bf16 v[52:55], v[144:147], v[160:163], v[52:55]
	v_mfma_f32_16x16x32_bf16 v[48:51], v[152:155], v[160:163], v[48:51]
	v_mfma_f32_16x16x32_bf16 v[36:39], v[144:147], v[168:171], v[36:39]
	v_mfma_f32_16x16x32_bf16 v[32:35], v[152:155], v[168:171], v[32:35]
	v_mfma_f32_16x16x32_bf16 v[20:23], v[144:147], v[176:179], v[20:23]
	v_mfma_f32_16x16x32_bf16 v[16:19], v[152:155], v[176:179], v[16:19]
	v_mfma_f32_16x16x32_bf16 v[4:7], v[144:147], v[196:199], v[4:7]
	v_mfma_f32_16x16x32_bf16 v[0:3], v[152:155], v[196:199], v[0:3]
	v_mfma_f32_16x16x32_bf16 v[52:55], v[148:151], v[164:167], v[52:55]
	v_mfma_f32_16x16x32_bf16 v[48:51], v[156:159], v[164:167], v[48:51]
	v_mfma_f32_16x16x32_bf16 v[36:39], v[148:151], v[172:175], v[36:39]
	v_mfma_f32_16x16x32_bf16 v[32:35], v[156:159], v[172:175], v[32:35]
	v_mfma_f32_16x16x32_bf16 v[20:23], v[148:151], v[180:183], v[20:23]
	v_mfma_f32_16x16x32_bf16 v[16:19], v[156:159], v[180:183], v[16:19]
	v_mfma_f32_16x16x32_bf16 v[4:7], v[148:151], v[200:203], v[4:7]
	v_mfma_f32_16x16x32_bf16 v[0:3], v[156:159], v[200:203], v[0:3]
	s_add_i32 s58, s58, 2
	s_add_u32 s2, s2, 0x100
	s_addc_u32 s3, s3, 0
	s_cmpk_gt_u32 s58, 0x7d
	s_waitcnt vmcnt(4)
	s_barrier
	s_cbranch_scc0 .LBB0_1194
	s_setprio 0
	s_and_b64 vcc, exec, s[22:23]
	s_cbranch_vccz .LBB0_1197
	s_barrier

.Lprio_skip9:
.LBB0_1324:
	ds_read_b128 v[140:143], v148
	ds_read_b128 v[154:157], v148 offset:1024
	ds_read_b128 v[158:161], v148 offset:2048
	ds_read_b128 v[162:165], v148 offset:3072
	ds_read_b128 v[166:169], v149
	ds_read_b128 v[170:173], v149 offset:1024
	ds_read_b128 v[174:177], v149 offset:2048
	ds_read_b128 v[178:181], v149 offset:3072
	s_add_u32 s34, s30, 0xfff80080
	s_addc_u32 s35, s31, -1
	s_cmp_eq_u32 s72, 28
	s_cselect_b32 s37, s66, s35
	s_cselect_b32 s36, s67, s34
	s_cselect_b32 s35, s68, s71
	s_cselect_b32 s34, s69, s70
	s_sub_u32 s98, s30, 0x80000
	s_subb_u32 s99, s31, 0
	s_add_i32 m0, s85, 0x8000
	ds_read_b128 v[182:185], v150
	ds_read_b128 v[186:189], v150 offset:1024
	ds_read_b128 v[190:193], v150 offset:2048
	ds_read_b128 v[194:197], v150 offset:3072
	ds_read_b128 v[198:201], v150 offset:4096
	ds_read_b128 v[202:205], v150 offset:5120
	ds_read_b128 v[206:209], v150 offset:6144
	ds_read_b128 v[210:213], v150 offset:7168
	global_load_lds_dwordx4 v222, s[98:99]
	s_add_u32 s98, s98, 0x20000
	s_addc_u32 s99, s99, 0
	s_add_i32 m0, s85, 0x9000
	s_nop 0
	global_load_lds_dwordx4 v222, s[98:99]
	s_add_u32 s98, s98, 0x20000
	s_addc_u32 s99, s99, 0
	s_add_i32 m0, s85, 0xa000
	s_nop 0
	global_load_lds_dwordx4 v222, s[98:99]
	s_add_u32 s98, s98, 0x20000
	s_addc_u32 s99, s99, 0
	s_add_i32 m0, s85, 0xb000
	s_nop 0
	global_load_lds_dwordx4 v222, s[98:99]
	s_waitcnt vmcnt(8)
	s_waitcnt lgkmcnt(0)
	s_barrier
	s_waitcnt lgkmcnt(0)
	v_mfma_f32_16x16x32_bf16 v[124:127], v[140:143], v[182:185], v[124:127]
	v_mfma_f32_16x16x32_bf16 v[120:123], v[158:161], v[182:185], v[120:123]
	v_mfma_f32_16x16x32_bf16 v[112:115], v[140:143], v[190:193], v[112:115]
	v_mfma_f32_16x16x32_bf16 v[104:107], v[158:161], v[190:193], v[104:107]
	v_mfma_f32_16x16x32_bf16 v[96:99], v[140:143], v[198:201], v[96:99]
	v_mfma_f32_16x16x32_bf16 v[88:91], v[158:161], v[198:201], v[88:91]
	v_mfma_f32_16x16x32_bf16 v[80:83], v[140:143], v[206:209], v[80:83]
	v_mfma_f32_16x16x32_bf16 v[72:75], v[158:161], v[206:209], v[72:75]
	v_mfma_f32_16x16x32_bf16 v[124:127], v[154:157], v[186:189], v[124:127]
	v_mfma_f32_16x16x32_bf16 v[120:123], v[162:165], v[186:189], v[120:123]
	v_mfma_f32_16x16x32_bf16 v[112:115], v[154:157], v[194:197], v[112:115]
	v_mfma_f32_16x16x32_bf16 v[104:107], v[162:165], v[194:197], v[104:107]
	v_mfma_f32_16x16x32_bf16 v[96:99], v[154:157], v[202:205], v[96:99]
	v_mfma_f32_16x16x32_bf16 v[88:91], v[162:165], v[202:205], v[88:91]
	v_mfma_f32_16x16x32_bf16 v[80:83], v[154:157], v[210:213], v[80:83]
	v_mfma_f32_16x16x32_bf16 v[72:75], v[162:165], v[210:213], v[72:75]
	v_mfma_f32_16x16x32_bf16 v[116:119], v[166:169], v[182:185], v[116:119]
	v_mfma_f32_16x16x32_bf16 v[108:111], v[174:177], v[182:185], v[108:111]
	v_mfma_f32_16x16x32_bf16 v[100:103], v[166:169], v[190:193], v[100:103]
	v_mfma_f32_16x16x32_bf16 v[92:95], v[174:177], v[190:193], v[92:95]
	v_mfma_f32_16x16x32_bf16 v[84:87], v[166:169], v[198:201], v[84:87]
	v_mfma_f32_16x16x32_bf16 v[76:79], v[174:177], v[198:201], v[76:79]
	v_mfma_f32_16x16x32_bf16 v[68:71], v[166:169], v[206:209], v[68:71]
	v_mfma_f32_16x16x32_bf16 v[64:67], v[174:177], v[206:209], v[64:67]
	v_mfma_f32_16x16x32_bf16 v[116:119], v[170:173], v[186:189], v[116:119]
	v_mfma_f32_16x16x32_bf16 v[108:111], v[178:181], v[186:189], v[108:111]
	v_mfma_f32_16x16x32_bf16 v[100:103], v[170:173], v[194:197], v[100:103]
	v_mfma_f32_16x16x32_bf16 v[92:95], v[178:181], v[194:197], v[92:95]
	v_mfma_f32_16x16x32_bf16 v[84:87], v[170:173], v[202:205], v[84:87]
	v_mfma_f32_16x16x32_bf16 v[76:79], v[178:181], v[202:205], v[76:79]
	v_mfma_f32_16x16x32_bf16 v[68:71], v[170:173], v[210:213], v[68:71]
	v_mfma_f32_16x16x32_bf16 v[64:67], v[178:181], v[210:213], v[64:67]
	s_barrier
	s_add_i32 s73, s56, s5
	v_lshl_add_u64 v[144:145], s[34:35], 0, v[130:131]
	s_mov_b32 m0, s73
	ds_read_b128 v[182:185], v150 offset:16384
	ds_read_b128 v[186:189], v150 offset:17408
	ds_read_b128 v[190:193], v150 offset:18432
	ds_read_b128 v[194:197], v150 offset:19456
	ds_read_b128 v[198:201], v150 offset:20480
	ds_read_b128 v[202:205], v150 offset:21504
	ds_read_b128 v[206:209], v150 offset:22528
	ds_read_b128 v[210:213], v150 offset:23552
	global_load_lds_dwordx4 v[144:145], off
	s_add_i32 m0, s73, 0x2000
	s_add_u32 s74, s34, 0x80000
	v_lshl_add_u64 v[214:215], s[34:35], 0, v[134:135]
	s_addc_u32 s75, s35, 0
	s_add_i32 s73, s57, s5
	global_load_lds_dwordx4 v[214:215], off
	v_lshl_add_u64 v[216:217], s[74:75], 0, v[130:131]
	s_mov_b32 m0, s73
	global_load_lds_dwordx4 v[216:217], off
	v_lshl_add_u64 v[216:217], s[74:75], 0, v[134:135]
	s_add_i32 m0, s73, 0x2000
	s_nop 0
	global_load_lds_dwordx4 v[216:217], off
	s_waitcnt vmcnt(8)
	s_waitcnt lgkmcnt(0)
	s_barrier
	s_waitcnt lgkmcnt(0)
	v_mfma_f32_16x16x32_bf16 v[60:63], v[140:143], v[182:185], v[60:63]
	v_mfma_f32_16x16x32_bf16 v[56:59], v[158:161], v[182:185], v[56:59]
	v_mfma_f32_16x16x32_bf16 v[48:51], v[140:143], v[190:193], v[48:51]
	v_mfma_f32_16x16x32_bf16 v[40:43], v[158:161], v[190:193], v[40:43]
	v_mfma_f32_16x16x32_bf16 v[32:35], v[140:143], v[198:201], v[32:35]
	v_mfma_f32_16x16x32_bf16 v[24:27], v[158:161], v[198:201], v[24:27]
	v_mfma_f32_16x16x32_bf16 v[16:19], v[140:143], v[206:209], v[16:19]
	v_mfma_f32_16x16x32_bf16 v[8:11], v[158:161], v[206:209], v[8:11]
	v_mfma_f32_16x16x32_bf16 v[60:63], v[154:157], v[186:189], v[60:63]
	v_mfma_f32_16x16x32_bf16 v[56:59], v[162:165], v[186:189], v[56:59]
	v_mfma_f32_16x16x32_bf16 v[48:51], v[154:157], v[194:197], v[48:51]
	v_mfma_f32_16x16x32_bf16 v[40:43], v[162:165], v[194:197], v[40:43]
	v_mfma_f32_16x16x32_bf16 v[32:35], v[154:157], v[202:205], v[32:35]
	v_mfma_f32_16x16x32_bf16 v[24:27], v[162:165], v[202:205], v[24:27]
	v_mfma_f32_16x16x32_bf16 v[16:19], v[154:157], v[210:213], v[16:19]
	v_mfma_f32_16x16x32_bf16 v[8:11], v[162:165], v[210:213], v[8:11]
	v_mfma_f32_16x16x32_bf16 v[52:55], v[166:169], v[182:185], v[52:55]
	v_mfma_f32_16x16x32_bf16 v[44:47], v[174:177], v[182:185], v[44:47]
	v_mfma_f32_16x16x32_bf16 v[36:39], v[166:169], v[190:193], v[36:39]
	v_mfma_f32_16x16x32_bf16 v[28:31], v[174:177], v[190:193], v[28:31]
	v_mfma_f32_16x16x32_bf16 v[20:23], v[166:169], v[198:201], v[20:23]
	v_mfma_f32_16x16x32_bf16 v[12:15], v[174:177], v[198:201], v[12:15]
	v_mfma_f32_16x16x32_bf16 v[4:7], v[166:169], v[206:209], v[4:7]
	v_mfma_f32_16x16x32_bf16 v[0:3], v[174:177], v[206:209], v[0:3]
	v_mfma_f32_16x16x32_bf16 v[52:55], v[170:173], v[186:189], v[52:55]
	v_mfma_f32_16x16x32_bf16 v[44:47], v[178:181], v[186:189], v[44:47]
	v_mfma_f32_16x16x32_bf16 v[36:39], v[170:173], v[194:197], v[36:39]
	v_mfma_f32_16x16x32_bf16 v[28:31], v[178:181], v[194:197], v[28:31]
	v_mfma_f32_16x16x32_bf16 v[20:23], v[170:173], v[202:205], v[20:23]
	v_mfma_f32_16x16x32_bf16 v[12:15], v[178:181], v[202:205], v[12:15]
	v_mfma_f32_16x16x32_bf16 v[4:7], v[170:173], v[210:213], v[4:7]
	v_mfma_f32_16x16x32_bf16 v[0:3], v[178:181], v[210:213], v[0:3]
	s_waitcnt vmcnt(4)
	s_barrier
	ds_read_b128 v[140:143], v151
	ds_read_b128 v[154:157], v151 offset:1024
	ds_read_b128 v[158:161], v151 offset:2048
	ds_read_b128 v[162:165], v151 offset:3072
	ds_read_b128 v[166:169], v152
	ds_read_b128 v[170:173], v152 offset:1024
	ds_read_b128 v[174:177], v152 offset:2048
	ds_read_b128 v[178:181], v152 offset:3072
	s_mov_b32 s98, s36
	s_mov_b32 s99, s37
	s_add_i32 m0, s85, 0
	ds_read_b128 v[182:185], v150 offset:32768
	ds_read_b128 v[186:189], v150 offset:33792
	ds_read_b128 v[190:193], v150 offset:34816
	ds_read_b128 v[194:197], v150 offset:35840
	ds_read_b128 v[198:201], v150 offset:36864
	ds_read_b128 v[202:205], v150 offset:37888
	ds_read_b128 v[206:209], v150 offset:38912
	ds_read_b128 v[210:213], v150 offset:39936
	global_load_lds_dwordx4 v222, s[98:99]
	s_add_u32 s98, s98, 0x20000
	s_addc_u32 s99, s99, 0
	s_add_i32 m0, s85, 0x1000
	s_nop 0
	global_load_lds_dwordx4 v222, s[98:99]
	s_add_u32 s98, s98, 0x20000
	s_addc_u32 s99, s99, 0
	s_add_i32 m0, s85, 0x2000
	s_nop 0
	global_load_lds_dwordx4 v222, s[98:99]
	s_add_u32 s98, s98, 0x20000
	s_addc_u32 s99, s99, 0
	s_add_i32 m0, s85, 0x3000
	s_nop 0
	global_load_lds_dwordx4 v222, s[98:99]
	s_waitcnt vmcnt(8)
	s_waitcnt lgkmcnt(0)
	s_barrier
	s_waitcnt lgkmcnt(0)
	v_mfma_f32_16x16x32_bf16 v[124:127], v[140:143], v[182:185], v[124:127]
	v_mfma_f32_16x16x32_bf16 v[120:123], v[158:161], v[182:185], v[120:123]
	v_mfma_f32_16x16x32_bf16 v[112:115], v[140:143], v[190:193], v[112:115]
	v_mfma_f32_16x16x32_bf16 v[104:107], v[158:161], v[190:193], v[104:107]
	v_mfma_f32_16x16x32_bf16 v[96:99], v[140:143], v[198:201], v[96:99]
	v_mfma_f32_16x16x32_bf16 v[88:91], v[158:161], v[198:201], v[88:91]
	v_mfma_f32_16x16x32_bf16 v[80:83], v[140:143], v[206:209], v[80:83]
	v_mfma_f32_16x16x32_bf16 v[72:75], v[158:161], v[206:209], v[72:75]
	v_mfma_f32_16x16x32_bf16 v[124:127], v[154:157], v[186:189], v[124:127]
	v_mfma_f32_16x16x32_bf16 v[120:123], v[162:165], v[186:189], v[120:123]
	v_mfma_f32_16x16x32_bf16 v[112:115], v[154:157], v[194:197], v[112:115]
	v_mfma_f32_16x16x32_bf16 v[104:107], v[162:165], v[194:197], v[104:107]
	v_mfma_f32_16x16x32_bf16 v[96:99], v[154:157], v[202:205], v[96:99]
	v_mfma_f32_16x16x32_bf16 v[88:91], v[162:165], v[202:205], v[88:91]
	v_mfma_f32_16x16x32_bf16 v[80:83], v[154:157], v[210:213], v[80:83]
	v_mfma_f32_16x16x32_bf16 v[72:75], v[162:165], v[210:213], v[72:75]
	v_mfma_f32_16x16x32_bf16 v[116:119], v[166:169], v[182:185], v[116:119]
	v_mfma_f32_16x16x32_bf16 v[108:111], v[174:177], v[182:185], v[108:111]
	v_mfma_f32_16x16x32_bf16 v[100:103], v[166:169], v[190:193], v[100:103]
	v_mfma_f32_16x16x32_bf16 v[92:95], v[174:177], v[190:193], v[92:95]
	v_mfma_f32_16x16x32_bf16 v[84:87], v[166:169], v[198:201], v[84:87]
	v_mfma_f32_16x16x32_bf16 v[76:79], v[174:177], v[198:201], v[76:79]
	v_mfma_f32_16x16x32_bf16 v[68:71], v[166:169], v[206:209], v[68:71]
	v_mfma_f32_16x16x32_bf16 v[64:67], v[174:177], v[206:209], v[64:67]
	v_mfma_f32_16x16x32_bf16 v[116:119], v[170:173], v[186:189], v[116:119]
	v_mfma_f32_16x16x32_bf16 v[108:111], v[178:181], v[186:189], v[108:111]
	v_mfma_f32_16x16x32_bf16 v[100:103], v[170:173], v[194:197], v[100:103]
	v_mfma_f32_16x16x32_bf16 v[92:95], v[178:181], v[194:197], v[92:95]
	v_mfma_f32_16x16x32_bf16 v[84:87], v[170:173], v[202:205], v[84:87]
	v_mfma_f32_16x16x32_bf16 v[76:79], v[178:181], v[202:205], v[76:79]
	v_mfma_f32_16x16x32_bf16 v[68:71], v[170:173], v[210:213], v[68:71]
	v_mfma_f32_16x16x32_bf16 v[64:67], v[178:181], v[210:213], v[64:67]
	s_barrier
	s_add_i32 s36, s58, s5
	v_lshl_add_u64 v[144:145], v[144:145], 0, s[10:11]
	s_mov_b32 m0, s36
	ds_read_b128 v[182:185], v150 offset:49152
	ds_read_b128 v[186:189], v150 offset:50176
	ds_read_b128 v[190:193], v150 offset:51200
	ds_read_b128 v[194:197], v150 offset:52224
	ds_read_b128 v[198:201], v150 offset:53248
	ds_read_b128 v[202:205], v150 offset:54272
	ds_read_b128 v[206:209], v150 offset:55296
	ds_read_b128 v[210:213], v150 offset:56320
	global_load_lds_dwordx4 v[144:145], off
	s_add_i32 m0, s36, 0x2000
	s_add_u32 s34, s34, 0x80080
	v_lshl_add_u64 v[144:145], v[214:215], 0, s[10:11]
	s_addc_u32 s35, s35, 0
	s_add_i32 s36, s59, s5
	global_load_lds_dwordx4 v[144:145], off
	v_lshl_add_u64 v[144:145], s[34:35], 0, v[130:131]
	s_mov_b32 m0, s36
	s_nop 0
	global_load_lds_dwordx4 v[144:145], off
	v_lshl_add_u64 v[144:145], s[34:35], 0, v[134:135]
	s_add_i32 m0, s36, 0x2000
	s_nop 0
	global_load_lds_dwordx4 v[144:145], off
	s_waitcnt vmcnt(8)
	s_waitcnt lgkmcnt(0)
	s_barrier
	s_waitcnt lgkmcnt(0)
	v_mfma_f32_16x16x32_bf16 v[60:63], v[140:143], v[182:185], v[60:63]
	v_mfma_f32_16x16x32_bf16 v[56:59], v[158:161], v[182:185], v[56:59]
	v_mfma_f32_16x16x32_bf16 v[48:51], v[140:143], v[190:193], v[48:51]
	v_mfma_f32_16x16x32_bf16 v[40:43], v[158:161], v[190:193], v[40:43]
	v_mfma_f32_16x16x32_bf16 v[32:35], v[140:143], v[198:201], v[32:35]
	v_mfma_f32_16x16x32_bf16 v[24:27], v[158:161], v[198:201], v[24:27]
	v_mfma_f32_16x16x32_bf16 v[16:19], v[140:143], v[206:209], v[16:19]
	v_mfma_f32_16x16x32_bf16 v[8:11], v[158:161], v[206:209], v[8:11]
	v_mfma_f32_16x16x32_bf16 v[60:63], v[154:157], v[186:189], v[60:63]
	v_mfma_f32_16x16x32_bf16 v[56:59], v[162:165], v[186:189], v[56:59]
	v_mfma_f32_16x16x32_bf16 v[48:51], v[154:157], v[194:197], v[48:51]
	v_mfma_f32_16x16x32_bf16 v[40:43], v[162:165], v[194:197], v[40:43]
	v_mfma_f32_16x16x32_bf16 v[32:35], v[154:157], v[202:205], v[32:35]
	v_mfma_f32_16x16x32_bf16 v[24:27], v[162:165], v[202:205], v[24:27]
	v_mfma_f32_16x16x32_bf16 v[16:19], v[154:157], v[210:213], v[16:19]
	v_mfma_f32_16x16x32_bf16 v[8:11], v[162:165], v[210:213], v[8:11]
	v_mfma_f32_16x16x32_bf16 v[52:55], v[166:169], v[182:185], v[52:55]
	v_mfma_f32_16x16x32_bf16 v[44:47], v[174:177], v[182:185], v[44:47]
	v_mfma_f32_16x16x32_bf16 v[36:39], v[166:169], v[190:193], v[36:39]
	v_mfma_f32_16x16x32_bf16 v[28:31], v[174:177], v[190:193], v[28:31]
	v_mfma_f32_16x16x32_bf16 v[20:23], v[166:169], v[198:201], v[20:23]
	v_mfma_f32_16x16x32_bf16 v[12:15], v[174:177], v[198:201], v[12:15]
	v_mfma_f32_16x16x32_bf16 v[4:7], v[166:169], v[206:209], v[4:7]
	v_mfma_f32_16x16x32_bf16 v[0:3], v[174:177], v[206:209], v[0:3]
	v_mfma_f32_16x16x32_bf16 v[52:55], v[170:173], v[186:189], v[52:55]
	v_mfma_f32_16x16x32_bf16 v[44:47], v[178:181], v[186:189], v[44:47]
	v_mfma_f32_16x16x32_bf16 v[36:39], v[170:173], v[194:197], v[36:39]
	v_mfma_f32_16x16x32_bf16 v[28:31], v[178:181], v[194:197], v[28:31]
	v_mfma_f32_16x16x32_bf16 v[20:23], v[170:173], v[202:205], v[20:23]
	v_mfma_f32_16x16x32_bf16 v[12:15], v[178:181], v[202:205], v[12:15]
	v_mfma_f32_16x16x32_bf16 v[4:7], v[170:173], v[210:213], v[4:7]
	v_mfma_f32_16x16x32_bf16 v[0:3], v[178:181], v[210:213], v[0:3]
	s_add_i32 s72, s72, 2
	s_add_u32 s30, s30, 0x100
	s_addc_u32 s31, s31, 0
	s_add_u32 s70, s70, 0x100
	s_addc_u32 s71, s71, 0
	s_cmp_gt_u32 s72, 29
	s_waitcnt vmcnt(4)
	s_barrier
	s_cbranch_scc0 .LBB0_1324
	s_setprio 0
	s_and_b64 vcc, exec, s[12:13]
	s_cbranch_vccz .LBB0_1327
	s_barrier

.Lprio_skip10:
.LBB0_1526:
	ds_read_b128 v[80:83], v185
	ds_read_b128 v[84:87], v185 offset:1024
	ds_read_b128 v[92:95], v185 offset:2048
	ds_read_b128 v[100:103], v185 offset:3072
	ds_read_b128 v[152:155], v186
	ds_read_b128 v[156:159], v186 offset:1024
	ds_read_b128 v[160:163], v186 offset:2048
	ds_read_b128 v[164:167], v186 offset:3072
	s_add_u32 s2, s0, 0xfff80080
	s_addc_u32 s3, s1, -1
	s_cmp_eq_u32 s58, 28
	s_cselect_b32 s31, s52, s3
	s_cselect_b32 s30, s53, s2
	s_cselect_b32 s3, s54, s57
	s_cselect_b32 s2, s55, s56
	s_sub_u32 s98, s0, 0x80000
	s_subb_u32 s99, s1, 0
	s_add_i32 m0, s85, 0x8000
	ds_read_b128 v[168:171], v187
	ds_read_b128 v[172:175], v187 offset:1024
	ds_read_b128 v[176:179], v187 offset:2048
	ds_read_b128 v[190:193], v187 offset:3072
	ds_read_b128 v[194:197], v187 offset:4096
	ds_read_b128 v[198:201], v187 offset:5120
	ds_read_b128 v[202:205], v187 offset:6144
	ds_read_b128 v[206:209], v187 offset:7168
	global_load_lds_dwordx4 v222, s[98:99]
	s_add_u32 s98, s98, 0x20000
	s_addc_u32 s99, s99, 0
	s_add_i32 m0, s85, 0x9000
	s_nop 0
	global_load_lds_dwordx4 v222, s[98:99]
	s_add_u32 s98, s98, 0x20000
	s_addc_u32 s99, s99, 0
	s_add_i32 m0, s85, 0xa000
	s_nop 0
	global_load_lds_dwordx4 v222, s[98:99]
	s_add_u32 s98, s98, 0x20000
	s_addc_u32 s99, s99, 0
	s_add_i32 m0, s85, 0xb000
	s_nop 0
	global_load_lds_dwordx4 v222, s[98:99]
	s_waitcnt vmcnt(8)
	s_waitcnt lgkmcnt(0)
	s_barrier
	s_waitcnt lgkmcnt(0)
	v_mfma_f32_16x16x32_bf16 v[136:139], v[80:83], v[168:171], v[136:139]
	v_mfma_f32_16x16x32_bf16 v[140:143], v[92:95], v[168:171], v[140:143]
	v_mfma_f32_16x16x32_bf16 v[120:123], v[80:83], v[176:179], v[120:123]
	v_mfma_f32_16x16x32_bf16 v[124:127], v[92:95], v[176:179], v[124:127]
	v_mfma_f32_16x16x32_bf16 v[104:107], v[80:83], v[194:197], v[104:107]
	v_mfma_f32_16x16x32_bf16 v[108:111], v[92:95], v[194:197], v[108:111]
	v_mfma_f32_16x16x32_bf16 v[72:75], v[80:83], v[202:205], v[72:75]
	v_mfma_f32_16x16x32_bf16 v[76:79], v[92:95], v[202:205], v[76:79]
	v_mfma_f32_16x16x32_bf16 v[136:139], v[84:87], v[172:175], v[136:139]
	v_mfma_f32_16x16x32_bf16 v[140:143], v[100:103], v[172:175], v[140:143]
	v_mfma_f32_16x16x32_bf16 v[120:123], v[84:87], v[190:193], v[120:123]
	v_mfma_f32_16x16x32_bf16 v[124:127], v[100:103], v[190:193], v[124:127]
	v_mfma_f32_16x16x32_bf16 v[104:107], v[84:87], v[198:201], v[104:107]
	v_mfma_f32_16x16x32_bf16 v[108:111], v[100:103], v[198:201], v[108:111]
	v_mfma_f32_16x16x32_bf16 v[72:75], v[84:87], v[206:209], v[72:75]
	v_mfma_f32_16x16x32_bf16 v[76:79], v[100:103], v[206:209], v[76:79]
	v_mfma_f32_16x16x32_bf16 v[128:131], v[152:155], v[168:171], v[128:131]
	v_mfma_f32_16x16x32_bf16 v[132:135], v[160:163], v[168:171], v[132:135]
	v_mfma_f32_16x16x32_bf16 v[112:115], v[152:155], v[176:179], v[112:115]
	v_mfma_f32_16x16x32_bf16 v[116:119], v[160:163], v[176:179], v[116:119]
	v_mfma_f32_16x16x32_bf16 v[88:91], v[152:155], v[194:197], v[88:91]
	v_mfma_f32_16x16x32_bf16 v[96:99], v[160:163], v[194:197], v[96:99]
	v_mfma_f32_16x16x32_bf16 v[64:67], v[152:155], v[202:205], v[64:67]
	v_mfma_f32_16x16x32_bf16 v[68:71], v[160:163], v[202:205], v[68:71]
	v_mfma_f32_16x16x32_bf16 v[128:131], v[156:159], v[172:175], v[128:131]
	v_mfma_f32_16x16x32_bf16 v[132:135], v[164:167], v[172:175], v[132:135]
	v_mfma_f32_16x16x32_bf16 v[112:115], v[156:159], v[190:193], v[112:115]
	v_mfma_f32_16x16x32_bf16 v[116:119], v[164:167], v[190:193], v[116:119]
	v_mfma_f32_16x16x32_bf16 v[88:91], v[156:159], v[198:201], v[88:91]
	v_mfma_f32_16x16x32_bf16 v[96:99], v[164:167], v[198:201], v[96:99]
	v_mfma_f32_16x16x32_bf16 v[64:67], v[156:159], v[206:209], v[64:67]
	v_mfma_f32_16x16x32_bf16 v[68:71], v[164:167], v[206:209], v[68:71]
	s_barrier
	s_add_i32 s59, s49, s39
	v_lshl_add_u64 v[180:181], s[2:3], 0, v[146:147]
	s_mov_b32 m0, s59
	ds_read_b128 v[168:171], v187 offset:16384
	ds_read_b128 v[172:175], v187 offset:17408
	ds_read_b128 v[176:179], v187 offset:18432
	ds_read_b128 v[190:193], v187 offset:19456
	ds_read_b128 v[194:197], v187 offset:20480
	ds_read_b128 v[198:201], v187 offset:21504
	ds_read_b128 v[202:205], v187 offset:22528
	ds_read_b128 v[206:209], v187 offset:23552
	global_load_lds_dwordx4 v[180:181], off
	s_add_i32 m0, s59, 0x2000
	s_add_u32 s60, s2, 0x80000
	v_lshl_add_u64 v[210:211], s[2:3], 0, v[144:145]
	s_addc_u32 s61, s3, 0
	s_add_i32 s59, s50, s39
	global_load_lds_dwordx4 v[210:211], off
	v_lshl_add_u64 v[212:213], s[60:61], 0, v[146:147]
	s_mov_b32 m0, s59
	global_load_lds_dwordx4 v[212:213], off
	v_lshl_add_u64 v[212:213], s[60:61], 0, v[144:145]
	s_add_i32 m0, s59, 0x2000
	s_nop 0
	global_load_lds_dwordx4 v[212:213], off
	s_waitcnt vmcnt(8)
	s_waitcnt lgkmcnt(0)
	s_barrier
	s_waitcnt lgkmcnt(0)
	v_mfma_f32_16x16x32_bf16 v[56:59], v[80:83], v[168:171], v[56:59]
	v_mfma_f32_16x16x32_bf16 v[60:63], v[92:95], v[168:171], v[60:63]
	v_mfma_f32_16x16x32_bf16 v[40:43], v[80:83], v[176:179], v[40:43]
	v_mfma_f32_16x16x32_bf16 v[44:47], v[92:95], v[176:179], v[44:47]
	v_mfma_f32_16x16x32_bf16 v[24:27], v[80:83], v[194:197], v[24:27]
	v_mfma_f32_16x16x32_bf16 v[28:31], v[92:95], v[194:197], v[28:31]
	v_mfma_f32_16x16x32_bf16 v[8:11], v[80:83], v[202:205], v[8:11]
	v_mfma_f32_16x16x32_bf16 v[12:15], v[92:95], v[202:205], v[12:15]
	v_mfma_f32_16x16x32_bf16 v[56:59], v[84:87], v[172:175], v[56:59]
	v_mfma_f32_16x16x32_bf16 v[60:63], v[100:103], v[172:175], v[60:63]
	v_mfma_f32_16x16x32_bf16 v[40:43], v[84:87], v[190:193], v[40:43]
	v_mfma_f32_16x16x32_bf16 v[44:47], v[100:103], v[190:193], v[44:47]
	v_mfma_f32_16x16x32_bf16 v[24:27], v[84:87], v[198:201], v[24:27]
	v_mfma_f32_16x16x32_bf16 v[28:31], v[100:103], v[198:201], v[28:31]
	v_mfma_f32_16x16x32_bf16 v[8:11], v[84:87], v[206:209], v[8:11]
	v_mfma_f32_16x16x32_bf16 v[12:15], v[100:103], v[206:209], v[12:15]
	v_mfma_f32_16x16x32_bf16 v[48:51], v[152:155], v[168:171], v[48:51]
	v_mfma_f32_16x16x32_bf16 v[52:55], v[160:163], v[168:171], v[52:55]
	v_mfma_f32_16x16x32_bf16 v[32:35], v[152:155], v[176:179], v[32:35]
	v_mfma_f32_16x16x32_bf16 v[36:39], v[160:163], v[176:179], v[36:39]
	v_mfma_f32_16x16x32_bf16 v[16:19], v[152:155], v[194:197], v[16:19]
	v_mfma_f32_16x16x32_bf16 v[20:23], v[160:163], v[194:197], v[20:23]
	v_mfma_f32_16x16x32_bf16 v[0:3], v[152:155], v[202:205], v[0:3]
	v_mfma_f32_16x16x32_bf16 v[4:7], v[160:163], v[202:205], v[4:7]
	v_mfma_f32_16x16x32_bf16 v[48:51], v[156:159], v[172:175], v[48:51]
	v_mfma_f32_16x16x32_bf16 v[52:55], v[164:167], v[172:175], v[52:55]
	v_mfma_f32_16x16x32_bf16 v[32:35], v[156:159], v[190:193], v[32:35]
	v_mfma_f32_16x16x32_bf16 v[36:39], v[164:167], v[190:193], v[36:39]
	v_mfma_f32_16x16x32_bf16 v[16:19], v[156:159], v[198:201], v[16:19]
	v_mfma_f32_16x16x32_bf16 v[20:23], v[164:167], v[198:201], v[20:23]
	v_mfma_f32_16x16x32_bf16 v[0:3], v[156:159], v[206:209], v[0:3]
	v_mfma_f32_16x16x32_bf16 v[4:7], v[164:167], v[206:209], v[4:7]
	s_waitcnt vmcnt(4)
	s_barrier
	s_add_i32 s59, 0, 0x18000
	s_add_i32 s60, 0, 0x1c000
	v_add_u32_e32 v100, s59, v184
	v_add_u32_e32 v164, s60, v184
	ds_read_b128 v[80:83], v100
	ds_read_b128 v[84:87], v100 offset:1024
	ds_read_b128 v[92:95], v100 offset:2048
	ds_read_b128 v[100:103], v100 offset:3072
	ds_read_b128 v[152:155], v164
	ds_read_b128 v[156:159], v164 offset:1024
	ds_read_b128 v[160:163], v164 offset:2048
	ds_read_b128 v[164:167], v164 offset:3072
	s_mov_b32 s98, s30
	s_mov_b32 s99, s31
	s_add_i32 m0, s85, 0
	ds_read_b128 v[168:171], v187 offset:32768
	ds_read_b128 v[172:175], v187 offset:33792
	ds_read_b128 v[176:179], v187 offset:34816
	ds_read_b128 v[190:193], v187 offset:35840
	ds_read_b128 v[194:197], v187 offset:36864
	ds_read_b128 v[198:201], v187 offset:37888
	ds_read_b128 v[202:205], v187 offset:38912
	ds_read_b128 v[206:209], v187 offset:39936
	global_load_lds_dwordx4 v222, s[98:99]
	s_add_u32 s98, s98, 0x20000
	s_addc_u32 s99, s99, 0
	s_add_i32 m0, s85, 0x1000
	s_nop 0
	global_load_lds_dwordx4 v222, s[98:99]
	s_add_u32 s98, s98, 0x20000
	s_addc_u32 s99, s99, 0
	s_add_i32 m0, s85, 0x2000
	s_nop 0
	global_load_lds_dwordx4 v222, s[98:99]
	s_add_u32 s98, s98, 0x20000
	s_addc_u32 s99, s99, 0
	s_add_i32 m0, s85, 0x3000
	s_nop 0
	global_load_lds_dwordx4 v222, s[98:99]
	s_waitcnt vmcnt(8)
	s_waitcnt lgkmcnt(0)
	s_barrier
	s_waitcnt lgkmcnt(0)
	v_mfma_f32_16x16x32_bf16 v[136:139], v[80:83], v[168:171], v[136:139]
	v_mfma_f32_16x16x32_bf16 v[140:143], v[92:95], v[168:171], v[140:143]
	v_mfma_f32_16x16x32_bf16 v[120:123], v[80:83], v[176:179], v[120:123]
	v_mfma_f32_16x16x32_bf16 v[124:127], v[92:95], v[176:179], v[124:127]
	v_mfma_f32_16x16x32_bf16 v[104:107], v[80:83], v[194:197], v[104:107]
	v_mfma_f32_16x16x32_bf16 v[108:111], v[92:95], v[194:197], v[108:111]
	v_mfma_f32_16x16x32_bf16 v[72:75], v[80:83], v[202:205], v[72:75]
	v_mfma_f32_16x16x32_bf16 v[76:79], v[92:95], v[202:205], v[76:79]
	v_mfma_f32_16x16x32_bf16 v[136:139], v[84:87], v[172:175], v[136:139]
	v_mfma_f32_16x16x32_bf16 v[140:143], v[100:103], v[172:175], v[140:143]
	v_mfma_f32_16x16x32_bf16 v[120:123], v[84:87], v[190:193], v[120:123]
	v_mfma_f32_16x16x32_bf16 v[124:127], v[100:103], v[190:193], v[124:127]
	v_mfma_f32_16x16x32_bf16 v[104:107], v[84:87], v[198:201], v[104:107]
	v_mfma_f32_16x16x32_bf16 v[108:111], v[100:103], v[198:201], v[108:111]
	v_mfma_f32_16x16x32_bf16 v[72:75], v[84:87], v[206:209], v[72:75]
	v_mfma_f32_16x16x32_bf16 v[76:79], v[100:103], v[206:209], v[76:79]
	v_mfma_f32_16x16x32_bf16 v[128:131], v[152:155], v[168:171], v[128:131]
	v_mfma_f32_16x16x32_bf16 v[132:135], v[160:163], v[168:171], v[132:135]
	v_mfma_f32_16x16x32_bf16 v[112:115], v[152:155], v[176:179], v[112:115]
	v_mfma_f32_16x16x32_bf16 v[116:119], v[160:163], v[176:179], v[116:119]
	v_mfma_f32_16x16x32_bf16 v[88:91], v[152:155], v[194:197], v[88:91]
	v_mfma_f32_16x16x32_bf16 v[96:99], v[160:163], v[194:197], v[96:99]
	v_mfma_f32_16x16x32_bf16 v[64:67], v[152:155], v[202:205], v[64:67]
	v_mfma_f32_16x16x32_bf16 v[68:71], v[160:163], v[202:205], v[68:71]
	v_mfma_f32_16x16x32_bf16 v[128:131], v[156:159], v[172:175], v[128:131]
	v_mfma_f32_16x16x32_bf16 v[132:135], v[164:167], v[172:175], v[132:135]
	v_mfma_f32_16x16x32_bf16 v[112:115], v[156:159], v[190:193], v[112:115]
	v_mfma_f32_16x16x32_bf16 v[116:119], v[164:167], v[190:193], v[116:119]
	v_mfma_f32_16x16x32_bf16 v[88:91], v[156:159], v[198:201], v[88:91]
	v_mfma_f32_16x16x32_bf16 v[96:99], v[164:167], v[198:201], v[96:99]
	v_mfma_f32_16x16x32_bf16 v[64:67], v[156:159], v[206:209], v[64:67]
	v_mfma_f32_16x16x32_bf16 v[68:71], v[164:167], v[206:209], v[68:71]
	s_barrier
	s_add_i32 s30, s59, s39
	v_lshl_add_u64 v[180:181], v[180:181], 0, s[20:21]
	s_mov_b32 m0, s30
	ds_read_b128 v[168:171], v187 offset:49152
	ds_read_b128 v[172:175], v187 offset:50176
	ds_read_b128 v[176:179], v187 offset:51200
	ds_read_b128 v[190:193], v187 offset:52224
	ds_read_b128 v[194:197], v187 offset:53248
	ds_read_b128 v[198:201], v187 offset:54272
	ds_read_b128 v[202:205], v187 offset:55296
	ds_read_b128 v[206:209], v187 offset:56320
	global_load_lds_dwordx4 v[180:181], off
	s_add_i32 m0, s30, 0x2000
	s_add_u32 s2, s2, 0x80080
	v_lshl_add_u64 v[180:181], v[210:211], 0, s[20:21]
	s_addc_u32 s3, s3, 0
	s_add_i32 s30, s60, s39
	global_load_lds_dwordx4 v[180:181], off
	v_lshl_add_u64 v[180:181], s[2:3], 0, v[146:147]
	s_mov_b32 m0, s30
	s_nop 0
	global_load_lds_dwordx4 v[180:181], off
	v_lshl_add_u64 v[180:181], s[2:3], 0, v[144:145]
	s_add_i32 m0, s30, 0x2000
	s_nop 0
	global_load_lds_dwordx4 v[180:181], off
	s_waitcnt vmcnt(8)
	s_waitcnt lgkmcnt(0)
	s_barrier
	s_waitcnt lgkmcnt(0)
	v_mfma_f32_16x16x32_bf16 v[56:59], v[80:83], v[168:171], v[56:59]
	v_mfma_f32_16x16x32_bf16 v[60:63], v[92:95], v[168:171], v[60:63]
	v_mfma_f32_16x16x32_bf16 v[40:43], v[80:83], v[176:179], v[40:43]
	v_mfma_f32_16x16x32_bf16 v[44:47], v[92:95], v[176:179], v[44:47]
	v_mfma_f32_16x16x32_bf16 v[24:27], v[80:83], v[194:197], v[24:27]
	v_mfma_f32_16x16x32_bf16 v[28:31], v[92:95], v[194:197], v[28:31]
	v_mfma_f32_16x16x32_bf16 v[8:11], v[80:83], v[202:205], v[8:11]
	v_mfma_f32_16x16x32_bf16 v[12:15], v[92:95], v[202:205], v[12:15]
	v_mfma_f32_16x16x32_bf16 v[56:59], v[84:87], v[172:175], v[56:59]
	v_mfma_f32_16x16x32_bf16 v[60:63], v[100:103], v[172:175], v[60:63]
	v_mfma_f32_16x16x32_bf16 v[40:43], v[84:87], v[190:193], v[40:43]
	v_mfma_f32_16x16x32_bf16 v[44:47], v[100:103], v[190:193], v[44:47]
	v_mfma_f32_16x16x32_bf16 v[24:27], v[84:87], v[198:201], v[24:27]
	v_mfma_f32_16x16x32_bf16 v[28:31], v[100:103], v[198:201], v[28:31]
	v_mfma_f32_16x16x32_bf16 v[8:11], v[84:87], v[206:209], v[8:11]
	v_mfma_f32_16x16x32_bf16 v[12:15], v[100:103], v[206:209], v[12:15]
	v_mfma_f32_16x16x32_bf16 v[48:51], v[152:155], v[168:171], v[48:51]
	v_mfma_f32_16x16x32_bf16 v[52:55], v[160:163], v[168:171], v[52:55]
	v_mfma_f32_16x16x32_bf16 v[32:35], v[152:155], v[176:179], v[32:35]
	v_mfma_f32_16x16x32_bf16 v[36:39], v[160:163], v[176:179], v[36:39]
	v_mfma_f32_16x16x32_bf16 v[16:19], v[152:155], v[194:197], v[16:19]
	v_mfma_f32_16x16x32_bf16 v[20:23], v[160:163], v[194:197], v[20:23]
	v_mfma_f32_16x16x32_bf16 v[0:3], v[152:155], v[202:205], v[0:3]
	v_mfma_f32_16x16x32_bf16 v[4:7], v[160:163], v[202:205], v[4:7]
	v_mfma_f32_16x16x32_bf16 v[48:51], v[156:159], v[172:175], v[48:51]
	v_mfma_f32_16x16x32_bf16 v[52:55], v[164:167], v[172:175], v[52:55]
	v_mfma_f32_16x16x32_bf16 v[32:35], v[156:159], v[190:193], v[32:35]
	v_mfma_f32_16x16x32_bf16 v[36:39], v[164:167], v[190:193], v[36:39]
	v_mfma_f32_16x16x32_bf16 v[16:19], v[156:159], v[198:201], v[16:19]
	v_mfma_f32_16x16x32_bf16 v[20:23], v[164:167], v[198:201], v[20:23]
	v_mfma_f32_16x16x32_bf16 v[0:3], v[156:159], v[206:209], v[0:3]
	v_mfma_f32_16x16x32_bf16 v[4:7], v[164:167], v[206:209], v[4:7]
	s_add_i32 s58, s58, 2
	s_add_u32 s0, s0, 0x100
	s_addc_u32 s1, s1, 0
	s_add_u32 s56, s56, 0x100
	s_addc_u32 s57, s57, 0
	s_cmp_gt_u32 s58, 29
	s_waitcnt vmcnt(4)
	s_barrier
	s_cbranch_scc0 .LBB0_1526
	s_setprio 0
	s_and_b64 vcc, exec, s[24:25]
	s_cbranch_vccz .LBB0_1529
	s_barrier

.Lprio_skip12:
.LBB0_1825:
	ds_read_b128 v[120:123], v230
	ds_read_b128 v[132:135], v230 offset:1024
	ds_read_b128 v[136:139], v230 offset:2048
	ds_read_b128 v[140:143], v230 offset:3072
	ds_read_b128 v[144:147], v231
	ds_read_b128 v[148:151], v231 offset:1024
	ds_read_b128 v[152:155], v231 offset:2048
	ds_read_b128 v[156:159], v231 offset:3072
	s_add_u32 s28, s0, s2
	s_addc_u32 s29, s1, s3
	s_cmpk_eq_i32 s2, 0x1000
	s_cselect_b32 s30, 0, s2
	s_cselect_b32 s31, 0, s3
	s_cselect_b32 s28, s57, s28
	s_cselect_b32 s29, s5, s29
	s_add_u32 s30, s10, s30
	s_addc_u32 s31, s11, s31
	s_add_u32 s98, s2, s86
	s_addc_u32 s99, s3, s87
	s_add_i32 m0, s85, 0x8000
	v_lshl_add_u64 v[204:205], v[192:193], 0, s[98:99]
	ds_read_b128 v[160:163], v232
	ds_read_b128 v[164:167], v232 offset:1024
	ds_read_b128 v[168:171], v232 offset:2048
	ds_read_b128 v[172:175], v232 offset:3072
	ds_read_b128 v[176:179], v232 offset:4096
	ds_read_b128 v[180:183], v232 offset:5120
	ds_read_b128 v[196:199], v232 offset:6144
	ds_read_b128 v[200:203], v232 offset:7168
	global_load_lds_dwordx4 v[204:205], off
	s_add_u32 s98, s98, 0x20000
	s_addc_u32 s99, s99, 0
	s_add_i32 m0, s85, 0x9000
	v_lshl_add_u64 v[204:205], v[192:193], 0, s[98:99]
	global_load_lds_dwordx4 v[204:205], off
	s_add_u32 s98, s98, 0x20000
	s_addc_u32 s99, s99, 0
	s_add_i32 m0, s85, 0xa000
	v_lshl_add_u64 v[204:205], v[192:193], 0, s[98:99]
	global_load_lds_dwordx4 v[204:205], off
	s_add_u32 s98, s98, 0x20000
	s_addc_u32 s99, s99, 0
	s_add_i32 m0, s85, 0xb000
	v_lshl_add_u64 v[204:205], v[192:193], 0, s[98:99]
	global_load_lds_dwordx4 v[204:205], off
	s_waitcnt vmcnt(8)
	s_waitcnt lgkmcnt(0)
	s_barrier
	s_waitcnt lgkmcnt(0)
	v_mfma_f32_16x16x32_bf16 v[128:131], v[120:123], v[160:163], v[128:131]
	v_mfma_f32_16x16x32_bf16 v[124:127], v[136:139], v[160:163], v[124:127]
	v_mfma_f32_16x16x32_bf16 v[108:111], v[120:123], v[168:171], v[108:111]
	v_mfma_f32_16x16x32_bf16 v[104:107], v[136:139], v[168:171], v[104:107]
	v_mfma_f32_16x16x32_bf16 v[92:95], v[120:123], v[176:179], v[92:95]
	v_mfma_f32_16x16x32_bf16 v[88:91], v[136:139], v[176:179], v[88:91]
	v_mfma_f32_16x16x32_bf16 v[76:79], v[120:123], v[196:199], v[76:79]
	v_mfma_f32_16x16x32_bf16 v[72:75], v[136:139], v[196:199], v[72:75]
	v_mfma_f32_16x16x32_bf16 v[128:131], v[132:135], v[164:167], v[128:131]
	v_mfma_f32_16x16x32_bf16 v[124:127], v[140:143], v[164:167], v[124:127]
	v_mfma_f32_16x16x32_bf16 v[108:111], v[132:135], v[172:175], v[108:111]
	v_mfma_f32_16x16x32_bf16 v[104:107], v[140:143], v[172:175], v[104:107]
	v_mfma_f32_16x16x32_bf16 v[92:95], v[132:135], v[180:183], v[92:95]
	v_mfma_f32_16x16x32_bf16 v[88:91], v[140:143], v[180:183], v[88:91]
	v_mfma_f32_16x16x32_bf16 v[76:79], v[132:135], v[200:203], v[76:79]
	v_mfma_f32_16x16x32_bf16 v[72:75], v[140:143], v[200:203], v[72:75]
	v_mfma_f32_16x16x32_bf16 v[116:119], v[144:147], v[160:163], v[116:119]
	v_mfma_f32_16x16x32_bf16 v[112:115], v[152:155], v[160:163], v[112:115]
	v_mfma_f32_16x16x32_bf16 v[100:103], v[144:147], v[168:171], v[100:103]
	v_mfma_f32_16x16x32_bf16 v[96:99], v[152:155], v[168:171], v[96:99]
	v_mfma_f32_16x16x32_bf16 v[84:87], v[144:147], v[176:179], v[84:87]
	v_mfma_f32_16x16x32_bf16 v[80:83], v[152:155], v[176:179], v[80:83]
	v_mfma_f32_16x16x32_bf16 v[68:71], v[144:147], v[196:199], v[68:71]
	v_mfma_f32_16x16x32_bf16 v[64:67], v[152:155], v[196:199], v[64:67]
	v_mfma_f32_16x16x32_bf16 v[116:119], v[148:151], v[164:167], v[116:119]
	v_mfma_f32_16x16x32_bf16 v[112:115], v[156:159], v[164:167], v[112:115]
	v_mfma_f32_16x16x32_bf16 v[100:103], v[148:151], v[172:175], v[100:103]
	v_mfma_f32_16x16x32_bf16 v[96:99], v[156:159], v[172:175], v[96:99]
	v_mfma_f32_16x16x32_bf16 v[84:87], v[148:151], v[180:183], v[84:87]
	v_mfma_f32_16x16x32_bf16 v[80:83], v[156:159], v[180:183], v[80:83]
	v_mfma_f32_16x16x32_bf16 v[68:71], v[148:151], v[200:203], v[68:71]
	v_mfma_f32_16x16x32_bf16 v[64:67], v[156:159], v[200:203], v[64:67]
	s_barrier
	s_mov_b32 m0, s50
	v_lshl_add_u64 v[204:205], s[28:29], 0, v[188:189]
	s_add_u32 s60, s28, 0x80000
	ds_read_b128 v[160:163], v232 offset:16384
	ds_read_b128 v[164:167], v232 offset:17408
	ds_read_b128 v[168:171], v232 offset:18432
	ds_read_b128 v[172:175], v232 offset:19456
	ds_read_b128 v[176:179], v232 offset:20480
	ds_read_b128 v[180:183], v232 offset:21504
	ds_read_b128 v[196:199], v232 offset:22528
	ds_read_b128 v[200:203], v232 offset:23552
	global_load_lds_dwordx4 v[204:205], off
	v_lshl_add_u64 v[206:207], s[28:29], 0, v[184:185]
	s_mov_b32 m0, s51
	s_addc_u32 s61, s29, 0
	global_load_lds_dwordx4 v[206:207], off
	v_lshl_add_u64 v[208:209], s[60:61], 0, v[188:189]
	s_mov_b32 m0, s52
	global_load_lds_dwordx4 v[208:209], off
	v_lshl_add_u64 v[208:209], s[60:61], 0, v[184:185]
	s_mov_b32 m0, s53
	s_nop 0
	global_load_lds_dwordx4 v[208:209], off
	s_waitcnt vmcnt(8)
	s_waitcnt lgkmcnt(0)
	s_barrier
	s_waitcnt lgkmcnt(0)
	v_mfma_f32_16x16x32_bf16 v[60:63], v[120:123], v[160:163], v[60:63]
	v_mfma_f32_16x16x32_bf16 v[56:59], v[136:139], v[160:163], v[56:59]
	v_mfma_f32_16x16x32_bf16 v[44:47], v[120:123], v[168:171], v[44:47]
	v_mfma_f32_16x16x32_bf16 v[40:43], v[136:139], v[168:171], v[40:43]
	v_mfma_f32_16x16x32_bf16 v[28:31], v[120:123], v[176:179], v[28:31]
	v_mfma_f32_16x16x32_bf16 v[24:27], v[136:139], v[176:179], v[24:27]
	v_mfma_f32_16x16x32_bf16 v[12:15], v[120:123], v[196:199], v[12:15]
	v_mfma_f32_16x16x32_bf16 v[8:11], v[136:139], v[196:199], v[8:11]
	v_mfma_f32_16x16x32_bf16 v[60:63], v[132:135], v[164:167], v[60:63]
	v_mfma_f32_16x16x32_bf16 v[56:59], v[140:143], v[164:167], v[56:59]
	v_mfma_f32_16x16x32_bf16 v[44:47], v[132:135], v[172:175], v[44:47]
	v_mfma_f32_16x16x32_bf16 v[40:43], v[140:143], v[172:175], v[40:43]
	v_mfma_f32_16x16x32_bf16 v[28:31], v[132:135], v[180:183], v[28:31]
	v_mfma_f32_16x16x32_bf16 v[24:27], v[140:143], v[180:183], v[24:27]
	v_mfma_f32_16x16x32_bf16 v[12:15], v[132:135], v[200:203], v[12:15]
	v_mfma_f32_16x16x32_bf16 v[8:11], v[140:143], v[200:203], v[8:11]
	v_mfma_f32_16x16x32_bf16 v[52:55], v[144:147], v[160:163], v[52:55]
	v_mfma_f32_16x16x32_bf16 v[48:51], v[152:155], v[160:163], v[48:51]
	v_mfma_f32_16x16x32_bf16 v[36:39], v[144:147], v[168:171], v[36:39]
	v_mfma_f32_16x16x32_bf16 v[32:35], v[152:155], v[168:171], v[32:35]
	v_mfma_f32_16x16x32_bf16 v[20:23], v[144:147], v[176:179], v[20:23]
	v_mfma_f32_16x16x32_bf16 v[16:19], v[152:155], v[176:179], v[16:19]
	v_mfma_f32_16x16x32_bf16 v[4:7], v[144:147], v[196:199], v[4:7]
	v_mfma_f32_16x16x32_bf16 v[0:3], v[152:155], v[196:199], v[0:3]
	v_mfma_f32_16x16x32_bf16 v[52:55], v[148:151], v[164:167], v[52:55]
	v_mfma_f32_16x16x32_bf16 v[48:51], v[156:159], v[164:167], v[48:51]
	v_mfma_f32_16x16x32_bf16 v[36:39], v[148:151], v[172:175], v[36:39]
	v_mfma_f32_16x16x32_bf16 v[32:35], v[156:159], v[172:175], v[32:35]
	v_mfma_f32_16x16x32_bf16 v[20:23], v[148:151], v[180:183], v[20:23]
	v_mfma_f32_16x16x32_bf16 v[16:19], v[156:159], v[180:183], v[16:19]
	v_mfma_f32_16x16x32_bf16 v[4:7], v[148:151], v[200:203], v[4:7]
	v_mfma_f32_16x16x32_bf16 v[0:3], v[156:159], v[200:203], v[0:3]
	s_waitcnt vmcnt(4)
	s_barrier
	ds_read_b128 v[120:123], v234
	ds_read_b128 v[132:135], v234 offset:1024
	ds_read_b128 v[136:139], v234 offset:2048
	ds_read_b128 v[140:143], v234 offset:3072
	ds_read_b128 v[144:147], v235
	ds_read_b128 v[148:151], v235 offset:1024
	ds_read_b128 v[152:155], v235 offset:2048
	ds_read_b128 v[156:159], v235 offset:3072
	s_add_u32 s98, s30, s96
	s_addc_u32 s99, s31, s97
	s_add_i32 m0, s85, 0
	v_lshl_add_u64 v[212:213], s[98:99], 0, v[190:191]
	ds_read_b128 v[160:163], v232 offset:32768
	ds_read_b128 v[164:167], v232 offset:33792
	ds_read_b128 v[168:171], v232 offset:34816
	ds_read_b128 v[172:175], v232 offset:35840
	ds_read_b128 v[176:179], v232 offset:36864
	ds_read_b128 v[180:183], v232 offset:37888
	ds_read_b128 v[196:199], v232 offset:38912
	ds_read_b128 v[200:203], v232 offset:39936
	global_load_lds_dwordx4 v[212:213], off
	s_add_u32 s98, s98, 0x20000
	s_addc_u32 s99, s99, 0
	s_add_i32 m0, s85, 0x1000
	v_lshl_add_u64 v[212:213], s[98:99], 0, v[190:191]
	global_load_lds_dwordx4 v[212:213], off
	s_add_u32 s98, s98, 0x20000
	s_addc_u32 s99, s99, 0
	s_add_i32 m0, s85, 0x2000
	v_lshl_add_u64 v[212:213], s[98:99], 0, v[190:191]
	global_load_lds_dwordx4 v[212:213], off
	s_add_u32 s98, s98, 0x20000
	s_addc_u32 s99, s99, 0
	s_add_i32 m0, s85, 0x3000
	v_lshl_add_u64 v[212:213], s[98:99], 0, v[190:191]
	global_load_lds_dwordx4 v[212:213], off
	s_waitcnt vmcnt(8)
	s_waitcnt lgkmcnt(0)
	s_barrier
	s_waitcnt lgkmcnt(0)
	v_mfma_f32_16x16x32_bf16 v[128:131], v[120:123], v[160:163], v[128:131]
	v_mfma_f32_16x16x32_bf16 v[124:127], v[136:139], v[160:163], v[124:127]
	v_mfma_f32_16x16x32_bf16 v[108:111], v[120:123], v[168:171], v[108:111]
	v_mfma_f32_16x16x32_bf16 v[104:107], v[136:139], v[168:171], v[104:107]
	v_mfma_f32_16x16x32_bf16 v[92:95], v[120:123], v[176:179], v[92:95]
	v_mfma_f32_16x16x32_bf16 v[88:91], v[136:139], v[176:179], v[88:91]
	v_mfma_f32_16x16x32_bf16 v[76:79], v[120:123], v[196:199], v[76:79]
	v_mfma_f32_16x16x32_bf16 v[72:75], v[136:139], v[196:199], v[72:75]
	v_mfma_f32_16x16x32_bf16 v[128:131], v[132:135], v[164:167], v[128:131]
	v_mfma_f32_16x16x32_bf16 v[124:127], v[140:143], v[164:167], v[124:127]
	v_mfma_f32_16x16x32_bf16 v[108:111], v[132:135], v[172:175], v[108:111]
	v_mfma_f32_16x16x32_bf16 v[104:107], v[140:143], v[172:175], v[104:107]
	v_mfma_f32_16x16x32_bf16 v[92:95], v[132:135], v[180:183], v[92:95]
	v_mfma_f32_16x16x32_bf16 v[88:91], v[140:143], v[180:183], v[88:91]
	v_mfma_f32_16x16x32_bf16 v[76:79], v[132:135], v[200:203], v[76:79]
	v_mfma_f32_16x16x32_bf16 v[72:75], v[140:143], v[200:203], v[72:75]
	v_mfma_f32_16x16x32_bf16 v[116:119], v[144:147], v[160:163], v[116:119]
	v_mfma_f32_16x16x32_bf16 v[112:115], v[152:155], v[160:163], v[112:115]
	v_mfma_f32_16x16x32_bf16 v[100:103], v[144:147], v[168:171], v[100:103]
	v_mfma_f32_16x16x32_bf16 v[96:99], v[152:155], v[168:171], v[96:99]
	v_mfma_f32_16x16x32_bf16 v[84:87], v[144:147], v[176:179], v[84:87]
	v_mfma_f32_16x16x32_bf16 v[80:83], v[152:155], v[176:179], v[80:83]
	v_mfma_f32_16x16x32_bf16 v[68:71], v[144:147], v[196:199], v[68:71]
	v_mfma_f32_16x16x32_bf16 v[64:67], v[152:155], v[196:199], v[64:67]
	v_mfma_f32_16x16x32_bf16 v[116:119], v[148:151], v[164:167], v[116:119]
	v_mfma_f32_16x16x32_bf16 v[112:115], v[156:159], v[164:167], v[112:115]
	v_mfma_f32_16x16x32_bf16 v[100:103], v[148:151], v[172:175], v[100:103]
	v_mfma_f32_16x16x32_bf16 v[96:99], v[156:159], v[172:175], v[96:99]
	v_mfma_f32_16x16x32_bf16 v[84:87], v[148:151], v[180:183], v[84:87]
	v_mfma_f32_16x16x32_bf16 v[80:83], v[156:159], v[180:183], v[80:83]
	v_mfma_f32_16x16x32_bf16 v[68:71], v[148:151], v[200:203], v[68:71]
	v_mfma_f32_16x16x32_bf16 v[64:67], v[156:159], v[200:203], v[64:67]
	s_barrier
	s_mov_b32 m0, s55
	v_lshl_add_u64 v[204:205], v[204:205], 0, s[18:19]
	ds_read_b128 v[160:163], v232 offset:49152
	ds_read_b128 v[164:167], v232 offset:50176
	ds_read_b128 v[168:171], v232 offset:51200
	ds_read_b128 v[172:175], v232 offset:52224
	ds_read_b128 v[176:179], v232 offset:53248
	ds_read_b128 v[180:183], v232 offset:54272
	ds_read_b128 v[196:199], v232 offset:55296
	ds_read_b128 v[200:203], v232 offset:56320
	global_load_lds_dwordx4 v[204:205], off
	s_add_i32 m0, s55, 0x2000
	s_add_u32 s28, s28, 0x80080
	v_lshl_add_u64 v[204:205], v[206:207], 0, s[18:19]
	s_addc_u32 s29, s29, 0
	s_add_i32 s30, s54, s37
	global_load_lds_dwordx4 v[204:205], off
	v_lshl_add_u64 v[204:205], s[28:29], 0, v[188:189]
	s_mov_b32 m0, s30
	s_nop 0
	global_load_lds_dwordx4 v[204:205], off
	v_lshl_add_u64 v[204:205], s[28:29], 0, v[184:185]
	s_add_i32 m0, s30, 0x2000
	s_nop 0
	global_load_lds_dwordx4 v[204:205], off
	s_waitcnt vmcnt(8)
	s_waitcnt lgkmcnt(0)
	s_barrier
	s_waitcnt lgkmcnt(0)
	v_mfma_f32_16x16x32_bf16 v[60:63], v[120:123], v[160:163], v[60:63]
	v_mfma_f32_16x16x32_bf16 v[56:59], v[136:139], v[160:163], v[56:59]
	v_mfma_f32_16x16x32_bf16 v[44:47], v[120:123], v[168:171], v[44:47]
	v_mfma_f32_16x16x32_bf16 v[40:43], v[136:139], v[168:171], v[40:43]
	v_mfma_f32_16x16x32_bf16 v[28:31], v[120:123], v[176:179], v[28:31]
	v_mfma_f32_16x16x32_bf16 v[24:27], v[136:139], v[176:179], v[24:27]
	v_mfma_f32_16x16x32_bf16 v[12:15], v[120:123], v[196:199], v[12:15]
	v_mfma_f32_16x16x32_bf16 v[8:11], v[136:139], v[196:199], v[8:11]
	v_mfma_f32_16x16x32_bf16 v[60:63], v[132:135], v[164:167], v[60:63]
	v_mfma_f32_16x16x32_bf16 v[56:59], v[140:143], v[164:167], v[56:59]
	v_mfma_f32_16x16x32_bf16 v[44:47], v[132:135], v[172:175], v[44:47]
	v_mfma_f32_16x16x32_bf16 v[40:43], v[140:143], v[172:175], v[40:43]
	v_mfma_f32_16x16x32_bf16 v[28:31], v[132:135], v[180:183], v[28:31]
	v_mfma_f32_16x16x32_bf16 v[24:27], v[140:143], v[180:183], v[24:27]
	v_mfma_f32_16x16x32_bf16 v[12:15], v[132:135], v[200:203], v[12:15]
	v_mfma_f32_16x16x32_bf16 v[8:11], v[140:143], v[200:203], v[8:11]
	v_mfma_f32_16x16x32_bf16 v[52:55], v[144:147], v[160:163], v[52:55]
	v_mfma_f32_16x16x32_bf16 v[48:51], v[152:155], v[160:163], v[48:51]
	v_mfma_f32_16x16x32_bf16 v[36:39], v[144:147], v[168:171], v[36:39]
	v_mfma_f32_16x16x32_bf16 v[32:35], v[152:155], v[168:171], v[32:35]
	v_mfma_f32_16x16x32_bf16 v[20:23], v[144:147], v[176:179], v[20:23]
	v_mfma_f32_16x16x32_bf16 v[16:19], v[152:155], v[176:179], v[16:19]
	v_mfma_f32_16x16x32_bf16 v[4:7], v[144:147], v[196:199], v[4:7]
	v_mfma_f32_16x16x32_bf16 v[0:3], v[152:155], v[196:199], v[0:3]
	v_mfma_f32_16x16x32_bf16 v[52:55], v[148:151], v[164:167], v[52:55]
	v_mfma_f32_16x16x32_bf16 v[48:51], v[156:159], v[164:167], v[48:51]
	v_mfma_f32_16x16x32_bf16 v[36:39], v[148:151], v[172:175], v[36:39]
	v_mfma_f32_16x16x32_bf16 v[32:35], v[156:159], v[172:175], v[32:35]
	v_mfma_f32_16x16x32_bf16 v[20:23], v[148:151], v[180:183], v[20:23]
	v_mfma_f32_16x16x32_bf16 v[16:19], v[156:159], v[180:183], v[16:19]
	v_mfma_f32_16x16x32_bf16 v[4:7], v[148:151], v[200:203], v[4:7]
	v_mfma_f32_16x16x32_bf16 v[0:3], v[156:159], v[200:203], v[0:3]
	s_add_i32 s58, s58, 2
	s_add_u32 s2, s2, 0x100
	s_addc_u32 s3, s3, 0
	s_cmp_gt_u32 s58, 29
	s_waitcnt vmcnt(4)
	s_barrier
	s_cbranch_scc0 .LBB0_1825
	s_setprio 0
	s_and_b64 vcc, exec, s[22:23]
	s_cbranch_vccz .LBB0_1828
	s_barrier

.Lprio_skip13:
.LBB0_1955:
	ds_read_b128 v[140:143], v150
	ds_read_b128 v[144:147], v150 offset:1024
	ds_read_b128 v[156:159], v150 offset:2048
	ds_read_b128 v[160:163], v150 offset:3072
	ds_read_b128 v[164:167], v151
	ds_read_b128 v[168:171], v151 offset:1024
	ds_read_b128 v[172:175], v151 offset:2048
	ds_read_b128 v[176:179], v151 offset:3072
	s_add_u32 s36, s0, 0xfff80080
	s_addc_u32 s37, s1, -1
	s_cmp_eq_u32 s74, 28
	s_cselect_b32 s39, s68, s37
	s_cselect_b32 s38, s69, s36
	s_cselect_b32 s37, s70, s73
	s_cselect_b32 s36, s71, s72
	s_sub_u32 s98, s0, 0x80000
	s_subb_u32 s99, s1, 0
	s_add_i32 m0, s85, 0x8000
	ds_read_b128 v[180:183], v152
	ds_read_b128 v[184:187], v152 offset:1024
	ds_read_b128 v[188:191], v152 offset:2048
	ds_read_b128 v[192:195], v152 offset:3072
	ds_read_b128 v[196:199], v152 offset:4096
	ds_read_b128 v[200:203], v152 offset:5120
	ds_read_b128 v[204:207], v152 offset:6144
	ds_read_b128 v[208:211], v152 offset:7168
	global_load_lds_dwordx4 v222, s[98:99]
	s_add_u32 s98, s98, 0x20000
	s_addc_u32 s99, s99, 0
	s_add_i32 m0, s85, 0x9000
	s_nop 0
	global_load_lds_dwordx4 v222, s[98:99]
	s_add_u32 s98, s98, 0x20000
	s_addc_u32 s99, s99, 0
	s_add_i32 m0, s85, 0xa000
	s_nop 0
	global_load_lds_dwordx4 v222, s[98:99]
	s_add_u32 s98, s98, 0x20000
	s_addc_u32 s99, s99, 0
	s_add_i32 m0, s85, 0xb000
	s_nop 0
	global_load_lds_dwordx4 v222, s[98:99]
	s_waitcnt vmcnt(8)
	s_waitcnt lgkmcnt(0)
	s_barrier
	s_waitcnt lgkmcnt(0)
	v_mfma_f32_16x16x32_bf16 v[124:127], v[140:143], v[180:183], v[124:127]
	v_mfma_f32_16x16x32_bf16 v[120:123], v[156:159], v[180:183], v[120:123]
	v_mfma_f32_16x16x32_bf16 v[108:111], v[140:143], v[188:191], v[108:111]
	v_mfma_f32_16x16x32_bf16 v[104:107], v[156:159], v[188:191], v[104:107]
	v_mfma_f32_16x16x32_bf16 v[92:95], v[140:143], v[196:199], v[92:95]
	v_mfma_f32_16x16x32_bf16 v[88:91], v[156:159], v[196:199], v[88:91]
	v_mfma_f32_16x16x32_bf16 v[76:79], v[140:143], v[204:207], v[76:79]
	v_mfma_f32_16x16x32_bf16 v[72:75], v[156:159], v[204:207], v[72:75]
	v_mfma_f32_16x16x32_bf16 v[124:127], v[144:147], v[184:187], v[124:127]
	v_mfma_f32_16x16x32_bf16 v[120:123], v[160:163], v[184:187], v[120:123]
	v_mfma_f32_16x16x32_bf16 v[108:111], v[144:147], v[192:195], v[108:111]
	v_mfma_f32_16x16x32_bf16 v[104:107], v[160:163], v[192:195], v[104:107]
	v_mfma_f32_16x16x32_bf16 v[92:95], v[144:147], v[200:203], v[92:95]
	v_mfma_f32_16x16x32_bf16 v[88:91], v[160:163], v[200:203], v[88:91]
	v_mfma_f32_16x16x32_bf16 v[76:79], v[144:147], v[208:211], v[76:79]
	v_mfma_f32_16x16x32_bf16 v[72:75], v[160:163], v[208:211], v[72:75]
	v_mfma_f32_16x16x32_bf16 v[116:119], v[164:167], v[180:183], v[116:119]
	v_mfma_f32_16x16x32_bf16 v[112:115], v[172:175], v[180:183], v[112:115]
	v_mfma_f32_16x16x32_bf16 v[100:103], v[164:167], v[188:191], v[100:103]
	v_mfma_f32_16x16x32_bf16 v[96:99], v[172:175], v[188:191], v[96:99]
	v_mfma_f32_16x16x32_bf16 v[84:87], v[164:167], v[196:199], v[84:87]
	v_mfma_f32_16x16x32_bf16 v[80:83], v[172:175], v[196:199], v[80:83]
	v_mfma_f32_16x16x32_bf16 v[68:71], v[164:167], v[204:207], v[68:71]
	v_mfma_f32_16x16x32_bf16 v[64:67], v[172:175], v[204:207], v[64:67]
	v_mfma_f32_16x16x32_bf16 v[116:119], v[168:171], v[184:187], v[116:119]
	v_mfma_f32_16x16x32_bf16 v[112:115], v[176:179], v[184:187], v[112:115]
	v_mfma_f32_16x16x32_bf16 v[100:103], v[168:171], v[192:195], v[100:103]
	v_mfma_f32_16x16x32_bf16 v[96:99], v[176:179], v[192:195], v[96:99]
	v_mfma_f32_16x16x32_bf16 v[84:87], v[168:171], v[200:203], v[84:87]
	v_mfma_f32_16x16x32_bf16 v[80:83], v[176:179], v[200:203], v[80:83]
	v_mfma_f32_16x16x32_bf16 v[68:71], v[168:171], v[208:211], v[68:71]
	v_mfma_f32_16x16x32_bf16 v[64:67], v[176:179], v[208:211], v[64:67]
	s_barrier
	s_add_i32 s75, s56, s7
	v_lshl_add_u64 v[212:213], s[36:37], 0, v[130:131]
	s_mov_b32 m0, s75
	ds_read_b128 v[180:183], v152 offset:16384
	ds_read_b128 v[184:187], v152 offset:17408
	ds_read_b128 v[188:191], v152 offset:18432
	ds_read_b128 v[192:195], v152 offset:19456
	ds_read_b128 v[196:199], v152 offset:20480
	ds_read_b128 v[200:203], v152 offset:21504
	ds_read_b128 v[204:207], v152 offset:22528
	ds_read_b128 v[208:211], v152 offset:23552
	global_load_lds_dwordx4 v[212:213], off
	s_add_i32 m0, s75, 0x2000
	s_add_u32 s76, s36, 0x80000
	v_lshl_add_u64 v[214:215], s[36:37], 0, v[134:135]
	s_addc_u32 s77, s37, 0
	s_add_i32 s75, s57, s7
	global_load_lds_dwordx4 v[214:215], off
	v_lshl_add_u64 v[216:217], s[76:77], 0, v[130:131]
	s_mov_b32 m0, s75
	global_load_lds_dwordx4 v[216:217], off
	v_lshl_add_u64 v[216:217], s[76:77], 0, v[134:135]
	s_add_i32 m0, s75, 0x2000
	s_nop 0
	global_load_lds_dwordx4 v[216:217], off
	s_waitcnt vmcnt(8)
	s_waitcnt lgkmcnt(0)
	s_barrier
	s_waitcnt lgkmcnt(0)
	v_mfma_f32_16x16x32_bf16 v[60:63], v[140:143], v[180:183], v[60:63]
	v_mfma_f32_16x16x32_bf16 v[56:59], v[156:159], v[180:183], v[56:59]
	v_mfma_f32_16x16x32_bf16 v[44:47], v[140:143], v[188:191], v[44:47]
	v_mfma_f32_16x16x32_bf16 v[40:43], v[156:159], v[188:191], v[40:43]
	v_mfma_f32_16x16x32_bf16 v[28:31], v[140:143], v[196:199], v[28:31]
	v_mfma_f32_16x16x32_bf16 v[24:27], v[156:159], v[196:199], v[24:27]
	v_mfma_f32_16x16x32_bf16 v[12:15], v[140:143], v[204:207], v[12:15]
	v_mfma_f32_16x16x32_bf16 v[8:11], v[156:159], v[204:207], v[8:11]
	v_mfma_f32_16x16x32_bf16 v[60:63], v[144:147], v[184:187], v[60:63]
	v_mfma_f32_16x16x32_bf16 v[56:59], v[160:163], v[184:187], v[56:59]
	v_mfma_f32_16x16x32_bf16 v[44:47], v[144:147], v[192:195], v[44:47]
	v_mfma_f32_16x16x32_bf16 v[40:43], v[160:163], v[192:195], v[40:43]
	v_mfma_f32_16x16x32_bf16 v[28:31], v[144:147], v[200:203], v[28:31]
	v_mfma_f32_16x16x32_bf16 v[24:27], v[160:163], v[200:203], v[24:27]
	v_mfma_f32_16x16x32_bf16 v[12:15], v[144:147], v[208:211], v[12:15]
	v_mfma_f32_16x16x32_bf16 v[8:11], v[160:163], v[208:211], v[8:11]
	v_mfma_f32_16x16x32_bf16 v[52:55], v[164:167], v[180:183], v[52:55]
	v_mfma_f32_16x16x32_bf16 v[48:51], v[172:175], v[180:183], v[48:51]
	v_mfma_f32_16x16x32_bf16 v[36:39], v[164:167], v[188:191], v[36:39]
	v_mfma_f32_16x16x32_bf16 v[32:35], v[172:175], v[188:191], v[32:35]
	v_mfma_f32_16x16x32_bf16 v[20:23], v[164:167], v[196:199], v[20:23]
	v_mfma_f32_16x16x32_bf16 v[16:19], v[172:175], v[196:199], v[16:19]
	v_mfma_f32_16x16x32_bf16 v[4:7], v[164:167], v[204:207], v[4:7]
	v_mfma_f32_16x16x32_bf16 v[0:3], v[172:175], v[204:207], v[0:3]
	v_mfma_f32_16x16x32_bf16 v[52:55], v[168:171], v[184:187], v[52:55]
	v_mfma_f32_16x16x32_bf16 v[48:51], v[176:179], v[184:187], v[48:51]
	v_mfma_f32_16x16x32_bf16 v[36:39], v[168:171], v[192:195], v[36:39]
	v_mfma_f32_16x16x32_bf16 v[32:35], v[176:179], v[192:195], v[32:35]
	v_mfma_f32_16x16x32_bf16 v[20:23], v[168:171], v[200:203], v[20:23]
	v_mfma_f32_16x16x32_bf16 v[16:19], v[176:179], v[200:203], v[16:19]
	v_mfma_f32_16x16x32_bf16 v[4:7], v[168:171], v[208:211], v[4:7]
	v_mfma_f32_16x16x32_bf16 v[0:3], v[176:179], v[208:211], v[0:3]
	s_waitcnt vmcnt(4)
	s_barrier
	ds_read_b128 v[140:143], v153
	ds_read_b128 v[144:147], v153 offset:1024
	ds_read_b128 v[156:159], v153 offset:2048
	ds_read_b128 v[160:163], v153 offset:3072
	ds_read_b128 v[164:167], v154
	ds_read_b128 v[168:171], v154 offset:1024
	ds_read_b128 v[172:175], v154 offset:2048
	ds_read_b128 v[176:179], v154 offset:3072
	s_mov_b32 s98, s38
	s_mov_b32 s99, s39
	s_add_i32 m0, s85, 0
	ds_read_b128 v[180:183], v152 offset:32768
	ds_read_b128 v[184:187], v152 offset:33792
	ds_read_b128 v[188:191], v152 offset:34816
	ds_read_b128 v[192:195], v152 offset:35840
	ds_read_b128 v[196:199], v152 offset:36864
	ds_read_b128 v[200:203], v152 offset:37888
	ds_read_b128 v[204:207], v152 offset:38912
	ds_read_b128 v[208:211], v152 offset:39936
	global_load_lds_dwordx4 v222, s[98:99]
	s_add_u32 s98, s98, 0x20000
	s_addc_u32 s99, s99, 0
	s_add_i32 m0, s85, 0x1000
	s_nop 0
	global_load_lds_dwordx4 v222, s[98:99]
	s_add_u32 s98, s98, 0x20000
	s_addc_u32 s99, s99, 0
	s_add_i32 m0, s85, 0x2000
	s_nop 0
	global_load_lds_dwordx4 v222, s[98:99]
	s_add_u32 s98, s98, 0x20000
	s_addc_u32 s99, s99, 0
	s_add_i32 m0, s85, 0x3000
	s_nop 0
	global_load_lds_dwordx4 v222, s[98:99]
	s_waitcnt vmcnt(8)
	s_waitcnt lgkmcnt(0)
	s_barrier
	s_waitcnt lgkmcnt(0)
	v_mfma_f32_16x16x32_bf16 v[124:127], v[140:143], v[180:183], v[124:127]
	v_mfma_f32_16x16x32_bf16 v[120:123], v[156:159], v[180:183], v[120:123]
	v_mfma_f32_16x16x32_bf16 v[108:111], v[140:143], v[188:191], v[108:111]
	v_mfma_f32_16x16x32_bf16 v[104:107], v[156:159], v[188:191], v[104:107]
	v_mfma_f32_16x16x32_bf16 v[92:95], v[140:143], v[196:199], v[92:95]
	v_mfma_f32_16x16x32_bf16 v[88:91], v[156:159], v[196:199], v[88:91]
	v_mfma_f32_16x16x32_bf16 v[76:79], v[140:143], v[204:207], v[76:79]
	v_mfma_f32_16x16x32_bf16 v[72:75], v[156:159], v[204:207], v[72:75]
	v_mfma_f32_16x16x32_bf16 v[124:127], v[144:147], v[184:187], v[124:127]
	v_mfma_f32_16x16x32_bf16 v[120:123], v[160:163], v[184:187], v[120:123]
	v_mfma_f32_16x16x32_bf16 v[108:111], v[144:147], v[192:195], v[108:111]
	v_mfma_f32_16x16x32_bf16 v[104:107], v[160:163], v[192:195], v[104:107]
	v_mfma_f32_16x16x32_bf16 v[92:95], v[144:147], v[200:203], v[92:95]
	v_mfma_f32_16x16x32_bf16 v[88:91], v[160:163], v[200:203], v[88:91]
	v_mfma_f32_16x16x32_bf16 v[76:79], v[144:147], v[208:211], v[76:79]
	v_mfma_f32_16x16x32_bf16 v[72:75], v[160:163], v[208:211], v[72:75]
	v_mfma_f32_16x16x32_bf16 v[116:119], v[164:167], v[180:183], v[116:119]
	v_mfma_f32_16x16x32_bf16 v[112:115], v[172:175], v[180:183], v[112:115]
	v_mfma_f32_16x16x32_bf16 v[100:103], v[164:167], v[188:191], v[100:103]
	v_mfma_f32_16x16x32_bf16 v[96:99], v[172:175], v[188:191], v[96:99]
	v_mfma_f32_16x16x32_bf16 v[84:87], v[164:167], v[196:199], v[84:87]
	v_mfma_f32_16x16x32_bf16 v[80:83], v[172:175], v[196:199], v[80:83]
	v_mfma_f32_16x16x32_bf16 v[68:71], v[164:167], v[204:207], v[68:71]
	v_mfma_f32_16x16x32_bf16 v[64:67], v[172:175], v[204:207], v[64:67]
	v_mfma_f32_16x16x32_bf16 v[116:119], v[168:171], v[184:187], v[116:119]
	v_mfma_f32_16x16x32_bf16 v[112:115], v[176:179], v[184:187], v[112:115]
	v_mfma_f32_16x16x32_bf16 v[100:103], v[168:171], v[192:195], v[100:103]
	v_mfma_f32_16x16x32_bf16 v[96:99], v[176:179], v[192:195], v[96:99]
	v_mfma_f32_16x16x32_bf16 v[84:87], v[168:171], v[200:203], v[84:87]
	v_mfma_f32_16x16x32_bf16 v[80:83], v[176:179], v[200:203], v[80:83]
	v_mfma_f32_16x16x32_bf16 v[68:71], v[168:171], v[208:211], v[68:71]
	v_mfma_f32_16x16x32_bf16 v[64:67], v[176:179], v[208:211], v[64:67]
	s_barrier
	s_add_i32 s38, s58, s7
	v_lshl_add_u64 v[212:213], v[212:213], 0, s[14:15]
	s_mov_b32 m0, s38
	ds_read_b128 v[180:183], v152 offset:49152
	ds_read_b128 v[184:187], v152 offset:50176
	ds_read_b128 v[188:191], v152 offset:51200
	ds_read_b128 v[192:195], v152 offset:52224
	ds_read_b128 v[196:199], v152 offset:53248
	ds_read_b128 v[200:203], v152 offset:54272
	ds_read_b128 v[204:207], v152 offset:55296
	ds_read_b128 v[208:211], v152 offset:56320
	global_load_lds_dwordx4 v[212:213], off
	s_add_i32 m0, s38, 0x2000
	s_add_u32 s36, s36, 0x80080
	v_lshl_add_u64 v[212:213], v[214:215], 0, s[14:15]
	s_addc_u32 s37, s37, 0
	s_add_i32 s38, s59, s7
	global_load_lds_dwordx4 v[212:213], off
	v_lshl_add_u64 v[212:213], s[36:37], 0, v[130:131]
	s_mov_b32 m0, s38
	s_nop 0
	global_load_lds_dwordx4 v[212:213], off
	v_lshl_add_u64 v[212:213], s[36:37], 0, v[134:135]
	s_add_i32 m0, s38, 0x2000
	s_nop 0
	global_load_lds_dwordx4 v[212:213], off
	s_waitcnt vmcnt(8)
	s_waitcnt lgkmcnt(0)
	s_barrier
	s_waitcnt lgkmcnt(0)
	v_mfma_f32_16x16x32_bf16 v[60:63], v[140:143], v[180:183], v[60:63]
	v_mfma_f32_16x16x32_bf16 v[56:59], v[156:159], v[180:183], v[56:59]
	v_mfma_f32_16x16x32_bf16 v[44:47], v[140:143], v[188:191], v[44:47]
	v_mfma_f32_16x16x32_bf16 v[40:43], v[156:159], v[188:191], v[40:43]
	v_mfma_f32_16x16x32_bf16 v[28:31], v[140:143], v[196:199], v[28:31]
	v_mfma_f32_16x16x32_bf16 v[24:27], v[156:159], v[196:199], v[24:27]
	v_mfma_f32_16x16x32_bf16 v[12:15], v[140:143], v[204:207], v[12:15]
	v_mfma_f32_16x16x32_bf16 v[8:11], v[156:159], v[204:207], v[8:11]
	v_mfma_f32_16x16x32_bf16 v[60:63], v[144:147], v[184:187], v[60:63]
	v_mfma_f32_16x16x32_bf16 v[56:59], v[160:163], v[184:187], v[56:59]
	v_mfma_f32_16x16x32_bf16 v[44:47], v[144:147], v[192:195], v[44:47]
	v_mfma_f32_16x16x32_bf16 v[40:43], v[160:163], v[192:195], v[40:43]
	v_mfma_f32_16x16x32_bf16 v[28:31], v[144:147], v[200:203], v[28:31]
	v_mfma_f32_16x16x32_bf16 v[24:27], v[160:163], v[200:203], v[24:27]
	v_mfma_f32_16x16x32_bf16 v[12:15], v[144:147], v[208:211], v[12:15]
	v_mfma_f32_16x16x32_bf16 v[8:11], v[160:163], v[208:211], v[8:11]
	v_mfma_f32_16x16x32_bf16 v[52:55], v[164:167], v[180:183], v[52:55]
	v_mfma_f32_16x16x32_bf16 v[48:51], v[172:175], v[180:183], v[48:51]
	v_mfma_f32_16x16x32_bf16 v[36:39], v[164:167], v[188:191], v[36:39]
	v_mfma_f32_16x16x32_bf16 v[32:35], v[172:175], v[188:191], v[32:35]
	v_mfma_f32_16x16x32_bf16 v[20:23], v[164:167], v[196:199], v[20:23]
	v_mfma_f32_16x16x32_bf16 v[16:19], v[172:175], v[196:199], v[16:19]
	v_mfma_f32_16x16x32_bf16 v[4:7], v[164:167], v[204:207], v[4:7]
	v_mfma_f32_16x16x32_bf16 v[0:3], v[172:175], v[204:207], v[0:3]
	v_mfma_f32_16x16x32_bf16 v[52:55], v[168:171], v[184:187], v[52:55]
	v_mfma_f32_16x16x32_bf16 v[48:51], v[176:179], v[184:187], v[48:51]
	v_mfma_f32_16x16x32_bf16 v[36:39], v[168:171], v[192:195], v[36:39]
	v_mfma_f32_16x16x32_bf16 v[32:35], v[176:179], v[192:195], v[32:35]
	v_mfma_f32_16x16x32_bf16 v[20:23], v[168:171], v[200:203], v[20:23]
	v_mfma_f32_16x16x32_bf16 v[16:19], v[176:179], v[200:203], v[16:19]
	v_mfma_f32_16x16x32_bf16 v[4:7], v[168:171], v[208:211], v[4:7]
	v_mfma_f32_16x16x32_bf16 v[0:3], v[176:179], v[208:211], v[0:3]
	s_add_i32 s74, s74, 2
	s_add_u32 s0, s0, 0x100
	s_addc_u32 s1, s1, 0
	s_add_u32 s72, s72, 0x100
	s_addc_u32 s73, s73, 0
	s_cmp_gt_u32 s74, 29
	s_waitcnt vmcnt(4)
	s_barrier
	s_cbranch_scc0 .LBB0_1955
	s_setprio 0
	s_and_b64 vcc, exec, s[16:17]
	s_cbranch_vccz .LBB0_1958
	s_barrier

.Lprio_skip14:
.LBB0_2063:
	v_add_u32_e32 v147, s33, v145
	ds_read_b128 v[148:151], v147
	ds_read_b128 v[152:155], v147 offset:1024
	ds_read_b128 v[156:159], v147 offset:2048
	ds_read_b128 v[160:163], v147 offset:3072
	v_add_u32_e32 v147, s45, v145
	s_add_u32 s24, s18, s22
	ds_read_b128 v[164:167], v147
	ds_read_b128 v[168:171], v147 offset:1024
	ds_read_b128 v[172:175], v147 offset:2048
	ds_read_b128 v[176:179], v147 offset:3072
	s_addc_u32 s25, s19, s23
	s_add_u32 s24, s24, 0x100
	s_addc_u32 s25, s25, 0
	s_add_u32 s63, s56, s22
	s_addc_u32 s64, s57, s23
	s_cmpk_eq_i32 s22, 0x3f00
	s_cselect_b32 s27, s58, s25
	s_cselect_b32 s26, s59, s24
	s_cselect_b32 s25, s60, s64
	s_cselect_b32 s24, s61, s63
	s_add_u32 s98, s22, s86
	s_addc_u32 s99, s23, s87
	s_add_i32 m0, s85, 0x8000
	v_lshl_add_u64 v[214:215], v[140:141], 0, s[98:99]
	ds_read_b128 v[180:183], v146
	ds_read_b128 v[184:187], v146 offset:1024
	ds_read_b128 v[188:191], v146 offset:2048
	ds_read_b128 v[192:195], v146 offset:3072
	ds_read_b128 v[196:199], v146 offset:4096
	ds_read_b128 v[202:205], v146 offset:5120
	ds_read_b128 v[206:209], v146 offset:6144
	ds_read_b128 v[210:213], v146 offset:7168
	global_load_lds_dwordx4 v[214:215], off
	s_add_u32 s98, s98, 0x80000
	s_addc_u32 s99, s99, 0
	s_add_i32 m0, s85, 0x9000
	v_lshl_add_u64 v[214:215], v[140:141], 0, s[98:99]
	global_load_lds_dwordx4 v[214:215], off
	s_add_u32 s98, s98, 0x80000
	s_addc_u32 s99, s99, 0
	s_add_i32 m0, s85, 0xa000
	v_lshl_add_u64 v[214:215], v[140:141], 0, s[98:99]
	global_load_lds_dwordx4 v[214:215], off
	s_add_u32 s98, s98, 0x80000
	s_addc_u32 s99, s99, 0
	s_add_i32 m0, s85, 0xb000
	v_lshl_add_u64 v[214:215], v[140:141], 0, s[98:99]
	global_load_lds_dwordx4 v[214:215], off
	s_waitcnt vmcnt(8)
	s_waitcnt lgkmcnt(0)
	s_barrier
	s_waitcnt lgkmcnt(0)
	v_mfma_f32_16x16x32_bf16 v[124:127], v[148:151], v[180:183], v[124:127]
	v_mfma_f32_16x16x32_bf16 v[120:123], v[156:159], v[180:183], v[120:123]
	v_mfma_f32_16x16x32_bf16 v[108:111], v[148:151], v[188:191], v[108:111]
	v_mfma_f32_16x16x32_bf16 v[104:107], v[156:159], v[188:191], v[104:107]
	v_mfma_f32_16x16x32_bf16 v[92:95], v[148:151], v[196:199], v[92:95]
	v_mfma_f32_16x16x32_bf16 v[88:91], v[156:159], v[196:199], v[88:91]
	v_mfma_f32_16x16x32_bf16 v[76:79], v[148:151], v[206:209], v[76:79]
	v_mfma_f32_16x16x32_bf16 v[72:75], v[156:159], v[206:209], v[72:75]
	v_mfma_f32_16x16x32_bf16 v[124:127], v[152:155], v[184:187], v[124:127]
	v_mfma_f32_16x16x32_bf16 v[120:123], v[160:163], v[184:187], v[120:123]
	v_mfma_f32_16x16x32_bf16 v[108:111], v[152:155], v[192:195], v[108:111]
	v_mfma_f32_16x16x32_bf16 v[104:107], v[160:163], v[192:195], v[104:107]
	v_mfma_f32_16x16x32_bf16 v[92:95], v[152:155], v[202:205], v[92:95]
	v_mfma_f32_16x16x32_bf16 v[88:91], v[160:163], v[202:205], v[88:91]
	v_mfma_f32_16x16x32_bf16 v[76:79], v[152:155], v[210:213], v[76:79]
	v_mfma_f32_16x16x32_bf16 v[72:75], v[160:163], v[210:213], v[72:75]
	v_mfma_f32_16x16x32_bf16 v[116:119], v[164:167], v[180:183], v[116:119]
	v_mfma_f32_16x16x32_bf16 v[112:115], v[172:175], v[180:183], v[112:115]
	v_mfma_f32_16x16x32_bf16 v[100:103], v[164:167], v[188:191], v[100:103]
	v_mfma_f32_16x16x32_bf16 v[96:99], v[172:175], v[188:191], v[96:99]
	v_mfma_f32_16x16x32_bf16 v[84:87], v[164:167], v[196:199], v[84:87]
	v_mfma_f32_16x16x32_bf16 v[80:83], v[172:175], v[196:199], v[80:83]
	v_mfma_f32_16x16x32_bf16 v[68:71], v[164:167], v[206:209], v[68:71]
	v_mfma_f32_16x16x32_bf16 v[64:67], v[172:175], v[206:209], v[64:67]
	v_mfma_f32_16x16x32_bf16 v[116:119], v[168:171], v[184:187], v[116:119]
	v_mfma_f32_16x16x32_bf16 v[112:115], v[176:179], v[184:187], v[112:115]
	v_mfma_f32_16x16x32_bf16 v[100:103], v[168:171], v[192:195], v[100:103]
	v_mfma_f32_16x16x32_bf16 v[96:99], v[176:179], v[192:195], v[96:99]
	v_mfma_f32_16x16x32_bf16 v[84:87], v[168:171], v[202:205], v[84:87]
	v_mfma_f32_16x16x32_bf16 v[80:83], v[176:179], v[202:205], v[80:83]
	v_mfma_f32_16x16x32_bf16 v[68:71], v[168:171], v[210:213], v[68:71]
	v_mfma_f32_16x16x32_bf16 v[64:67], v[176:179], v[210:213], v[64:67]
	s_barrier
	s_mov_b32 m0, s48
	v_lshl_add_u64 v[214:215], s[24:25], 0, v[132:133]
	s_add_u32 s64, s24, 0x200000
	ds_read_b128 v[180:183], v146 offset:16384
	ds_read_b128 v[184:187], v146 offset:17408
	ds_read_b128 v[188:191], v146 offset:18432
	ds_read_b128 v[192:195], v146 offset:19456
	ds_read_b128 v[196:199], v146 offset:20480
	ds_read_b128 v[202:205], v146 offset:21504
	ds_read_b128 v[206:209], v146 offset:22528
	ds_read_b128 v[210:213], v146 offset:23552
	global_load_lds_dwordx4 v[214:215], off
	v_lshl_add_u64 v[216:217], s[24:25], 0, v[128:129]
	s_mov_b32 m0, s49
	s_addc_u32 s65, s25, 0
	global_load_lds_dwordx4 v[216:217], off
	v_lshl_add_u64 v[218:219], s[64:65], 0, v[132:133]
	s_mov_b32 m0, s50
	global_load_lds_dwordx4 v[218:219], off
	v_lshl_add_u64 v[218:219], s[64:65], 0, v[128:129]
	s_mov_b32 m0, s51
	s_nop 0
	global_load_lds_dwordx4 v[218:219], off
	s_waitcnt vmcnt(8)
	s_waitcnt lgkmcnt(0)
	s_barrier
	s_waitcnt lgkmcnt(0)
	v_mfma_f32_16x16x32_bf16 v[60:63], v[148:151], v[180:183], v[60:63]
	v_mfma_f32_16x16x32_bf16 v[56:59], v[156:159], v[180:183], v[56:59]
	v_mfma_f32_16x16x32_bf16 v[44:47], v[148:151], v[188:191], v[44:47]
	v_mfma_f32_16x16x32_bf16 v[40:43], v[156:159], v[188:191], v[40:43]
	v_mfma_f32_16x16x32_bf16 v[28:31], v[148:151], v[196:199], v[28:31]
	v_mfma_f32_16x16x32_bf16 v[24:27], v[156:159], v[196:199], v[24:27]
	v_mfma_f32_16x16x32_bf16 v[12:15], v[148:151], v[206:209], v[12:15]
	v_mfma_f32_16x16x32_bf16 v[8:11], v[156:159], v[206:209], v[8:11]
	v_mfma_f32_16x16x32_bf16 v[60:63], v[152:155], v[184:187], v[60:63]
	v_mfma_f32_16x16x32_bf16 v[56:59], v[160:163], v[184:187], v[56:59]
	v_mfma_f32_16x16x32_bf16 v[44:47], v[152:155], v[192:195], v[44:47]
	v_mfma_f32_16x16x32_bf16 v[40:43], v[160:163], v[192:195], v[40:43]
	v_mfma_f32_16x16x32_bf16 v[28:31], v[152:155], v[202:205], v[28:31]
	v_mfma_f32_16x16x32_bf16 v[24:27], v[160:163], v[202:205], v[24:27]
	v_mfma_f32_16x16x32_bf16 v[12:15], v[152:155], v[210:213], v[12:15]
	v_mfma_f32_16x16x32_bf16 v[8:11], v[160:163], v[210:213], v[8:11]
	v_mfma_f32_16x16x32_bf16 v[52:55], v[164:167], v[180:183], v[52:55]
	v_mfma_f32_16x16x32_bf16 v[48:51], v[172:175], v[180:183], v[48:51]
	v_mfma_f32_16x16x32_bf16 v[36:39], v[164:167], v[188:191], v[36:39]
	v_mfma_f32_16x16x32_bf16 v[32:35], v[172:175], v[188:191], v[32:35]
	v_mfma_f32_16x16x32_bf16 v[20:23], v[164:167], v[196:199], v[20:23]
	v_mfma_f32_16x16x32_bf16 v[16:19], v[172:175], v[196:199], v[16:19]
	v_mfma_f32_16x16x32_bf16 v[4:7], v[164:167], v[206:209], v[4:7]
	v_mfma_f32_16x16x32_bf16 v[0:3], v[172:175], v[206:209], v[0:3]
	v_mfma_f32_16x16x32_bf16 v[52:55], v[168:171], v[184:187], v[52:55]
	v_mfma_f32_16x16x32_bf16 v[48:51], v[176:179], v[184:187], v[48:51]
	v_mfma_f32_16x16x32_bf16 v[36:39], v[168:171], v[192:195], v[36:39]
	v_mfma_f32_16x16x32_bf16 v[32:35], v[176:179], v[192:195], v[32:35]
	v_mfma_f32_16x16x32_bf16 v[20:23], v[168:171], v[202:205], v[20:23]
	v_mfma_f32_16x16x32_bf16 v[16:19], v[176:179], v[202:205], v[16:19]
	v_mfma_f32_16x16x32_bf16 v[4:7], v[168:171], v[210:213], v[4:7]
	v_mfma_f32_16x16x32_bf16 v[0:3], v[176:179], v[210:213], v[0:3]
	s_waitcnt vmcnt(4)
	s_barrier
	v_add_u32_e32 v147, s52, v145
	s_add_i32 s63, 0, 0x1c000
	ds_read_b128 v[148:151], v147
	ds_read_b128 v[152:155], v147 offset:1024
	ds_read_b128 v[156:159], v147 offset:2048
	ds_read_b128 v[160:163], v147 offset:3072
	v_add_u32_e32 v147, s63, v145
	ds_read_b128 v[164:167], v147
	ds_read_b128 v[168:171], v147 offset:1024
	ds_read_b128 v[172:175], v147 offset:2048
	ds_read_b128 v[176:179], v147 offset:3072
	s_add_u32 s98, s26, s96
	s_addc_u32 s99, s27, s97
	s_add_i32 m0, s85, 0
	v_lshl_add_u64 v[222:223], s[98:99], 0, v[134:135]
	ds_read_b128 v[180:183], v146 offset:32768
	ds_read_b128 v[184:187], v146 offset:33792
	ds_read_b128 v[188:191], v146 offset:34816
	ds_read_b128 v[192:195], v146 offset:35840
	ds_read_b128 v[196:199], v146 offset:36864
	ds_read_b128 v[202:205], v146 offset:37888
	ds_read_b128 v[206:209], v146 offset:38912
	ds_read_b128 v[210:213], v146 offset:39936
	global_load_lds_dwordx4 v[222:223], off
	s_add_u32 s98, s98, 0x80000
	s_addc_u32 s99, s99, 0
	s_add_i32 m0, s85, 0x1000
	v_lshl_add_u64 v[222:223], s[98:99], 0, v[134:135]
	global_load_lds_dwordx4 v[222:223], off
	s_add_u32 s98, s98, 0x80000
	s_addc_u32 s99, s99, 0
	s_add_i32 m0, s85, 0x2000
	v_lshl_add_u64 v[222:223], s[98:99], 0, v[134:135]
	global_load_lds_dwordx4 v[222:223], off
	s_add_u32 s98, s98, 0x80000
	s_addc_u32 s99, s99, 0
	s_add_i32 m0, s85, 0x3000
	v_lshl_add_u64 v[222:223], s[98:99], 0, v[134:135]
	global_load_lds_dwordx4 v[222:223], off
	s_waitcnt vmcnt(8)
	s_waitcnt lgkmcnt(0)
	s_barrier
	s_waitcnt lgkmcnt(0)
	v_mfma_f32_16x16x32_bf16 v[124:127], v[148:151], v[180:183], v[124:127]
	v_mfma_f32_16x16x32_bf16 v[120:123], v[156:159], v[180:183], v[120:123]
	v_mfma_f32_16x16x32_bf16 v[108:111], v[148:151], v[188:191], v[108:111]
	v_mfma_f32_16x16x32_bf16 v[104:107], v[156:159], v[188:191], v[104:107]
	v_mfma_f32_16x16x32_bf16 v[92:95], v[148:151], v[196:199], v[92:95]
	v_mfma_f32_16x16x32_bf16 v[88:91], v[156:159], v[196:199], v[88:91]
	v_mfma_f32_16x16x32_bf16 v[76:79], v[148:151], v[206:209], v[76:79]
	v_mfma_f32_16x16x32_bf16 v[72:75], v[156:159], v[206:209], v[72:75]
	v_mfma_f32_16x16x32_bf16 v[124:127], v[152:155], v[184:187], v[124:127]
	v_mfma_f32_16x16x32_bf16 v[120:123], v[160:163], v[184:187], v[120:123]
	v_mfma_f32_16x16x32_bf16 v[108:111], v[152:155], v[192:195], v[108:111]
	v_mfma_f32_16x16x32_bf16 v[104:107], v[160:163], v[192:195], v[104:107]
	v_mfma_f32_16x16x32_bf16 v[92:95], v[152:155], v[202:205], v[92:95]
	v_mfma_f32_16x16x32_bf16 v[88:91], v[160:163], v[202:205], v[88:91]
	v_mfma_f32_16x16x32_bf16 v[76:79], v[152:155], v[210:213], v[76:79]
	v_mfma_f32_16x16x32_bf16 v[72:75], v[160:163], v[210:213], v[72:75]
	v_mfma_f32_16x16x32_bf16 v[116:119], v[164:167], v[180:183], v[116:119]
	v_mfma_f32_16x16x32_bf16 v[112:115], v[172:175], v[180:183], v[112:115]
	v_mfma_f32_16x16x32_bf16 v[100:103], v[164:167], v[188:191], v[100:103]
	v_mfma_f32_16x16x32_bf16 v[96:99], v[172:175], v[188:191], v[96:99]
	v_mfma_f32_16x16x32_bf16 v[84:87], v[164:167], v[196:199], v[84:87]
	v_mfma_f32_16x16x32_bf16 v[80:83], v[172:175], v[196:199], v[80:83]
	v_mfma_f32_16x16x32_bf16 v[68:71], v[164:167], v[206:209], v[68:71]
	v_mfma_f32_16x16x32_bf16 v[64:67], v[172:175], v[206:209], v[64:67]
	v_mfma_f32_16x16x32_bf16 v[116:119], v[168:171], v[184:187], v[116:119]
	v_mfma_f32_16x16x32_bf16 v[112:115], v[176:179], v[184:187], v[112:115]
	v_mfma_f32_16x16x32_bf16 v[100:103], v[168:171], v[192:195], v[100:103]
	v_mfma_f32_16x16x32_bf16 v[96:99], v[176:179], v[192:195], v[96:99]
	v_mfma_f32_16x16x32_bf16 v[84:87], v[168:171], v[202:205], v[84:87]
	v_mfma_f32_16x16x32_bf16 v[80:83], v[176:179], v[202:205], v[80:83]
	v_mfma_f32_16x16x32_bf16 v[68:71], v[168:171], v[210:213], v[68:71]
	v_mfma_f32_16x16x32_bf16 v[64:67], v[176:179], v[210:213], v[64:67]
	s_barrier
	s_add_i32 s26, s52, s38
	v_lshl_add_u64 v[214:215], v[214:215], 0, s[8:9]
	s_mov_b32 m0, s26
	ds_read_b128 v[180:183], v146 offset:49152
	ds_read_b128 v[184:187], v146 offset:50176
	ds_read_b128 v[188:191], v146 offset:51200
	ds_read_b128 v[192:195], v146 offset:52224
	ds_read_b128 v[196:199], v146 offset:53248
	ds_read_b128 v[202:205], v146 offset:54272
	ds_read_b128 v[206:209], v146 offset:55296
	ds_read_b128 v[210:213], v146 offset:56320
	global_load_lds_dwordx4 v[214:215], off
	s_add_i32 m0, s26, 0x2000
	s_add_u32 s24, s24, 0x200080
	v_lshl_add_u64 v[214:215], v[216:217], 0, s[8:9]
	s_addc_u32 s25, s25, 0
	s_add_i32 s26, s63, s38
	global_load_lds_dwordx4 v[214:215], off
	v_lshl_add_u64 v[214:215], s[24:25], 0, v[132:133]
	s_mov_b32 m0, s26
	s_nop 0
	global_load_lds_dwordx4 v[214:215], off
	v_lshl_add_u64 v[214:215], s[24:25], 0, v[128:129]
	s_add_i32 m0, s26, 0x2000
	s_nop 0
	global_load_lds_dwordx4 v[214:215], off
	s_waitcnt vmcnt(8)
	s_waitcnt lgkmcnt(0)
	s_barrier
	s_waitcnt lgkmcnt(0)
	v_mfma_f32_16x16x32_bf16 v[60:63], v[148:151], v[180:183], v[60:63]
	v_mfma_f32_16x16x32_bf16 v[56:59], v[156:159], v[180:183], v[56:59]
	v_mfma_f32_16x16x32_bf16 v[44:47], v[148:151], v[188:191], v[44:47]
	v_mfma_f32_16x16x32_bf16 v[40:43], v[156:159], v[188:191], v[40:43]
	v_mfma_f32_16x16x32_bf16 v[28:31], v[148:151], v[196:199], v[28:31]
	v_mfma_f32_16x16x32_bf16 v[24:27], v[156:159], v[196:199], v[24:27]
	v_mfma_f32_16x16x32_bf16 v[12:15], v[148:151], v[206:209], v[12:15]
	v_mfma_f32_16x16x32_bf16 v[8:11], v[156:159], v[206:209], v[8:11]
	v_mfma_f32_16x16x32_bf16 v[60:63], v[152:155], v[184:187], v[60:63]
	v_mfma_f32_16x16x32_bf16 v[56:59], v[160:163], v[184:187], v[56:59]
	v_mfma_f32_16x16x32_bf16 v[44:47], v[152:155], v[192:195], v[44:47]
	v_mfma_f32_16x16x32_bf16 v[40:43], v[160:163], v[192:195], v[40:43]
	v_mfma_f32_16x16x32_bf16 v[28:31], v[152:155], v[202:205], v[28:31]
	v_mfma_f32_16x16x32_bf16 v[24:27], v[160:163], v[202:205], v[24:27]
	v_mfma_f32_16x16x32_bf16 v[12:15], v[152:155], v[210:213], v[12:15]
	v_mfma_f32_16x16x32_bf16 v[8:11], v[160:163], v[210:213], v[8:11]
	v_mfma_f32_16x16x32_bf16 v[52:55], v[164:167], v[180:183], v[52:55]
	v_mfma_f32_16x16x32_bf16 v[48:51], v[172:175], v[180:183], v[48:51]
	v_mfma_f32_16x16x32_bf16 v[36:39], v[164:167], v[188:191], v[36:39]
	v_mfma_f32_16x16x32_bf16 v[32:35], v[172:175], v[188:191], v[32:35]
	v_mfma_f32_16x16x32_bf16 v[20:23], v[164:167], v[196:199], v[20:23]
	v_mfma_f32_16x16x32_bf16 v[16:19], v[172:175], v[196:199], v[16:19]
	v_mfma_f32_16x16x32_bf16 v[4:7], v[164:167], v[206:209], v[4:7]
	v_mfma_f32_16x16x32_bf16 v[0:3], v[172:175], v[206:209], v[0:3]
	v_mfma_f32_16x16x32_bf16 v[52:55], v[168:171], v[184:187], v[52:55]
	v_mfma_f32_16x16x32_bf16 v[48:51], v[176:179], v[184:187], v[48:51]
	v_mfma_f32_16x16x32_bf16 v[36:39], v[168:171], v[192:195], v[36:39]
	v_mfma_f32_16x16x32_bf16 v[32:35], v[176:179], v[192:195], v[32:35]
	v_mfma_f32_16x16x32_bf16 v[20:23], v[168:171], v[202:205], v[20:23]
	v_mfma_f32_16x16x32_bf16 v[16:19], v[176:179], v[202:205], v[16:19]
	v_mfma_f32_16x16x32_bf16 v[4:7], v[168:171], v[210:213], v[4:7]
	v_mfma_f32_16x16x32_bf16 v[0:3], v[176:179], v[210:213], v[0:3]
	s_add_i32 s62, s62, 2
	s_add_u32 s22, s22, 0x100
	s_addc_u32 s23, s23, 0
	s_cmpk_gt_u32 s62, 0x7d
	s_waitcnt vmcnt(4)
	s_barrier
	s_cbranch_scc0 .LBB0_2063
	s_setprio 0
	s_and_b64 vcc, exec, s[10:11]
	s_cbranch_vccz .LBB0_2066
	s_barrier
